# P3 epilogue: residual loads issued ahead in rolling VGPR buffers; PEER phase: workgroup barrier per table slice + soft per-XCD rendezvous per token block (L2 locality)
# speedup vs baseline: 1.0064x; 1.0029x over previous
; __device__ __forceinline__ unsigned cvt_pk_bf16(float lo, float hi) { unsigned r; asm volatile("v_cvt_pk_bf16_f32 %0, %1, %2" : "=v"(r) : "v"(lo), "v"(hi)); return r; }
;     __device__ __forceinline__ void operator()(const f32x4 (&acc)[2][2][4][2], const Unit& u, int wr, int wc, int fr, int fq) const {
; #pragma unroll
;         for (int ai = 0; ai < 2; ++ai)
; #pragma unroll
;             for (int m = 0; m < 4; ++m) {
;                 const int row = u.pm * BM + ai * HALF + wr * 64 + m * 16 + fr;
;                 const float* xr = xrow(xp, xs, row);
; #pragma unroll
;                 for (int bj = 0; bj < 2; ++bj) {
;                     const int col = u.pn * BM + bj * HALF + wc * 32 + 8 * fq;
;                     const f32x4 x0 = *(const f32x4*)(xr + col), x1v = *(const f32x4*)(xr + col + 4);
;                     const f32x4 v0 = acc[ai][bj][m][0] + x0, v1 = acc[ai][bj][m][1] + x1v;
;                     u32x4 w; w.x = cvt_pk_bf16(v0[0], v0[1]); w.y = cvt_pk_bf16(v0[2], v0[3]); w.z = cvt_pk_bf16(v1[0], v1[1]); w.w = cvt_pk_bf16(v1[2], v1[3]);
;                     *(u32x4*)(X1B + (size_t)row * D + col) = w;
;                 }
;             }
.LBB0_516:
	v_lshl_add_u32 v144, s26, 8, v150
	v_lshl_or_b32 v146, s48, 8, v152
	v_ashrrev_i32_e32 v147, 31, v146
	v_lshlrev_b64 v[148:149], 2, v[146:147]
	v_lshlrev_b64 v[146:147], 1, v[146:147]
	v_mov_b32_e32 v226, s19
	v_mov_b32_e32 v227, s17
	v_mov_b32_e32 v190, s18
	v_mov_b32_e32 v191, s16
	v_mov_b32_e32 v156, v144
	v_cmp_gt_i32_e32 vcc, s41, v156
	v_add_u32_e32 v145, 0xffffc000, v156
	v_ashrrev_i32_e32 v157, 31, v156
	v_cndmask_b32_e32 v157, 0, v157, vcc
	v_cndmask_b32_e32 v156, v145, v156, vcc
	v_cndmask_b32_e32 v255, v226, v227, vcc
	v_cndmask_b32_e32 v254, v190, v191, vcc
	v_lshlrev_b64 v[156:157], 12, v[156:157]
	v_lshl_add_u64 v[156:157], v[254:255], 0, v[156:157]
	v_lshl_add_u64 v[156:157], v[156:157], 0, v[148:149]
	v_add_u32_e32 v158, 0x10, v144
	v_cmp_gt_i32_e32 vcc, s41, v158
	v_add_u32_e32 v145, 0xffffc000, v158
	v_ashrrev_i32_e32 v159, 31, v158
	v_cndmask_b32_e32 v159, 0, v159, vcc
	v_cndmask_b32_e32 v158, v145, v158, vcc
	v_cndmask_b32_e32 v255, v226, v227, vcc
	v_cndmask_b32_e32 v254, v190, v191, vcc
	v_lshlrev_b64 v[158:159], 12, v[158:159]
	v_lshl_add_u64 v[158:159], v[254:255], 0, v[158:159]
	v_lshl_add_u64 v[158:159], v[158:159], 0, v[148:149]
	v_add_u32_e32 v160, 0x20, v144
	v_cmp_gt_i32_e32 vcc, s41, v160
	v_add_u32_e32 v145, 0xffffc000, v160
	v_ashrrev_i32_e32 v161, 31, v160
	v_cndmask_b32_e32 v161, 0, v161, vcc
	v_cndmask_b32_e32 v160, v145, v160, vcc
	v_cndmask_b32_e32 v255, v226, v227, vcc
	v_cndmask_b32_e32 v254, v190, v191, vcc
	v_lshlrev_b64 v[160:161], 12, v[160:161]
	v_lshl_add_u64 v[160:161], v[254:255], 0, v[160:161]
	v_lshl_add_u64 v[160:161], v[160:161], 0, v[148:149]
	v_add_u32_e32 v162, 0x30, v144
	v_cmp_gt_i32_e32 vcc, s41, v162
	v_add_u32_e32 v145, 0xffffc000, v162
	v_ashrrev_i32_e32 v163, 31, v162
	v_cndmask_b32_e32 v163, 0, v163, vcc
	v_cndmask_b32_e32 v162, v145, v162, vcc
	v_cndmask_b32_e32 v255, v226, v227, vcc
	v_cndmask_b32_e32 v254, v190, v191, vcc
	v_lshlrev_b64 v[162:163], 12, v[162:163]
	v_lshl_add_u64 v[162:163], v[254:255], 0, v[162:163]
	v_lshl_add_u64 v[162:163], v[162:163], 0, v[148:149]
	v_add_u32_e32 v164, 0x80, v144
	v_cmp_gt_i32_e32 vcc, s41, v164
	v_add_u32_e32 v145, 0xffffc000, v164
	v_ashrrev_i32_e32 v165, 31, v164
	v_cndmask_b32_e32 v165, 0, v165, vcc
	v_cndmask_b32_e32 v164, v145, v164, vcc
	v_cndmask_b32_e32 v255, v226, v227, vcc
	v_cndmask_b32_e32 v254, v190, v191, vcc
	v_lshlrev_b64 v[164:165], 12, v[164:165]
	v_lshl_add_u64 v[164:165], v[254:255], 0, v[164:165]
	v_lshl_add_u64 v[164:165], v[164:165], 0, v[148:149]
	v_add_u32_e32 v166, 0x90, v144
	v_cmp_gt_i32_e32 vcc, s41, v166
	v_add_u32_e32 v145, 0xffffc000, v166
	v_ashrrev_i32_e32 v167, 31, v166
	v_cndmask_b32_e32 v167, 0, v167, vcc
	v_cndmask_b32_e32 v166, v145, v166, vcc
	v_cndmask_b32_e32 v255, v226, v227, vcc
	v_cndmask_b32_e32 v254, v190, v191, vcc
	v_lshlrev_b64 v[166:167], 12, v[166:167]
	v_lshl_add_u64 v[166:167], v[254:255], 0, v[166:167]
	v_lshl_add_u64 v[166:167], v[166:167], 0, v[148:149]
	v_add_u32_e32 v168, 0xa0, v144
	v_cmp_gt_i32_e32 vcc, s41, v168
	v_add_u32_e32 v145, 0xffffc000, v168
	v_ashrrev_i32_e32 v169, 31, v168
	v_cndmask_b32_e32 v169, 0, v169, vcc
	v_cndmask_b32_e32 v168, v145, v168, vcc
	v_cndmask_b32_e32 v255, v226, v227, vcc
	v_cndmask_b32_e32 v254, v190, v191, vcc
	v_lshlrev_b64 v[168:169], 12, v[168:169]
	v_lshl_add_u64 v[168:169], v[254:255], 0, v[168:169]
	v_lshl_add_u64 v[168:169], v[168:169], 0, v[148:149]
	v_add_u32_e32 v170, 0xb0, v144
	v_cmp_gt_i32_e32 vcc, s41, v170
	v_add_u32_e32 v145, 0xffffc000, v170
	v_ashrrev_i32_e32 v171, 31, v170
	v_cndmask_b32_e32 v171, 0, v171, vcc
	v_cndmask_b32_e32 v170, v145, v170, vcc
	v_cndmask_b32_e32 v255, v226, v227, vcc
	v_cndmask_b32_e32 v254, v190, v191, vcc
	v_lshlrev_b64 v[170:171], 12, v[170:171]
	v_lshl_add_u64 v[170:171], v[254:255], 0, v[170:171]
	v_lshl_add_u64 v[170:171], v[170:171], 0, v[148:149]
	global_load_dwordx4 v[172:175], v[156:157], off
	global_load_dwordx4 v[176:179], v[156:157], off offset:16
	global_load_dwordx4 v[182:185], v[156:157], off offset:512
	global_load_dwordx4 v[186:189], v[156:157], off offset:528
	global_load_dwordx4 v[194:197], v[158:159], off
	global_load_dwordx4 v[198:201], v[158:159], off offset:16
	global_load_dwordx4 v[202:205], v[158:159], off offset:512
	global_load_dwordx4 v[206:209], v[158:159], off offset:528
	global_load_dwordx4 v[210:213], v[160:161], off
	global_load_dwordx4 v[214:217], v[160:161], off offset:16
	global_load_dwordx4 v[218:221], v[160:161], off offset:512
	global_load_dwordx4 v[222:225], v[160:161], off offset:528
	global_load_dwordx4 v[228:231], v[162:163], off
	global_load_dwordx4 v[232:235], v[162:163], off offset:16
	global_load_dwordx4 v[236:239], v[162:163], off offset:512
	global_load_dwordx4 v[240:243], v[162:163], off offset:528
	global_load_dwordx4 v[244:247], v[164:165], off
	global_load_dwordx4 v[248:251], v[164:165], off offset:16
	v_mov_b32_e32 v254, v144
	v_ashrrev_i32_e32 v255, 31, v254
	v_lshlrev_b64 v[254:255], 11, v[254:255]
	v_lshl_add_u64 v[254:255], s[20:21], 0, v[254:255]
	v_lshl_add_u64 v[254:255], v[254:255], 0, v[146:147]
	s_waitcnt vmcnt(16)
	v_pk_add_f32 v[172:173], v[124:125], v[172:173]
	v_pk_add_f32 v[174:175], v[126:127], v[174:175]
	v_pk_add_f32 v[176:177], v[120:121], v[176:177]
	v_pk_add_f32 v[178:179], v[122:123], v[178:179]
	v_cvt_pk_bf16_f32 v120, v172, v173
	v_cvt_pk_bf16_f32 v121, v174, v175
	v_cvt_pk_bf16_f32 v122, v176, v177
	v_cvt_pk_bf16_f32 v123, v178, v179
	global_store_dwordx4 v[254:255], v[120:123], off
	global_load_dwordx4 v[172:175], v[164:165], off offset:512
	global_load_dwordx4 v[176:179], v[164:165], off offset:528
	s_waitcnt vmcnt(17)
; __device__ __forceinline__ unsigned cvt_pk_bf16(float lo, float hi) { unsigned r; asm volatile("v_cvt_pk_bf16_f32 %0, %1, %2" : "=v"(r) : "v"(lo), "v"(hi)); return r; }
;     __device__ __forceinline__ void operator()(const f32x4 (&acc)[2][2][4][2], const Unit& u, int wr, int wc, int fr, int fq) const {
;     ...
;         for (int ai = 0; ai < 2; ++ai)
; #pragma unroll
;             for (int m = 0; m < 4; ++m) {
;                 const int row = u.pm * BM + ai * HALF + wr * 64 + m * 16 + fr;
;                 const float* xr = xrow(xp, xs, row);
; #pragma unroll
;                 for (int bj = 0; bj < 2; ++bj) {
;                     const int col = u.pn * BM + bj * HALF + wc * 32 + 8 * fq;
;                     const f32x4 x0 = *(const f32x4*)(xr + col), x1v = *(const f32x4*)(xr + col + 4);
;                     const f32x4 v0 = acc[ai][bj][m][0] + x0, v1 = acc[ai][bj][m][1] + x1v;
;                     u32x4 w; w.x = cvt_pk_bf16(v0[0], v0[1]); w.y = cvt_pk_bf16(v0[2], v0[3]); w.z = cvt_pk_bf16(v1[0], v1[1]); w.w = cvt_pk_bf16(v1[2], v1[3]);
;                     *(u32x4*)(X1B + (size_t)row * D + col) = w;
;                 }
;             }
	v_pk_add_f32 v[182:183], v[116:117], v[182:183]
	v_pk_add_f32 v[184:185], v[118:119], v[184:185]
	v_pk_add_f32 v[186:187], v[112:113], v[186:187]
	v_pk_add_f32 v[188:189], v[114:115], v[188:189]
	v_cvt_pk_bf16_f32 v112, v182, v183
	v_cvt_pk_bf16_f32 v113, v184, v185
	v_cvt_pk_bf16_f32 v114, v186, v187
	v_cvt_pk_bf16_f32 v115, v188, v189
	global_store_dwordx4 v[254:255], v[112:115], off offset:256
	global_load_dwordx4 v[182:185], v[166:167], off
	global_load_dwordx4 v[186:189], v[166:167], off offset:16
	v_add_u32_e32 v254, 0x10, v144
	v_ashrrev_i32_e32 v255, 31, v254
	v_lshlrev_b64 v[254:255], 11, v[254:255]
	v_lshl_add_u64 v[254:255], s[20:21], 0, v[254:255]
	v_lshl_add_u64 v[254:255], v[254:255], 0, v[146:147]
	s_waitcnt vmcnt(18)
	v_pk_add_f32 v[194:195], v[108:109], v[194:195]
	v_pk_add_f32 v[196:197], v[110:111], v[196:197]
	v_pk_add_f32 v[198:199], v[104:105], v[198:199]
	v_pk_add_f32 v[200:201], v[106:107], v[200:201]
	v_cvt_pk_bf16_f32 v104, v194, v195
	v_cvt_pk_bf16_f32 v105, v196, v197
	v_cvt_pk_bf16_f32 v106, v198, v199
	v_cvt_pk_bf16_f32 v107, v200, v201
	global_store_dwordx4 v[254:255], v[104:107], off
	global_load_dwordx4 v[194:197], v[166:167], off offset:512
	global_load_dwordx4 v[198:201], v[166:167], off offset:528
	s_waitcnt vmcnt(19)
	v_pk_add_f32 v[202:203], v[100:101], v[202:203]
	v_pk_add_f32 v[204:205], v[102:103], v[204:205]
	v_pk_add_f32 v[206:207], v[96:97], v[206:207]
	v_pk_add_f32 v[208:209], v[98:99], v[208:209]
	v_cvt_pk_bf16_f32 v96, v202, v203
	v_cvt_pk_bf16_f32 v97, v204, v205
	v_cvt_pk_bf16_f32 v98, v206, v207
	v_cvt_pk_bf16_f32 v99, v208, v209
	global_store_dwordx4 v[254:255], v[96:99], off offset:256
	global_load_dwordx4 v[202:205], v[168:169], off
	global_load_dwordx4 v[206:209], v[168:169], off offset:16
	v_add_u32_e32 v254, 0x20, v144
	v_ashrrev_i32_e32 v255, 31, v254
	v_lshlrev_b64 v[254:255], 11, v[254:255]
	v_lshl_add_u64 v[254:255], s[20:21], 0, v[254:255]
	v_lshl_add_u64 v[254:255], v[254:255], 0, v[146:147]
	s_waitcnt vmcnt(20)
	v_pk_add_f32 v[210:211], v[92:93], v[210:211]
	v_pk_add_f32 v[212:213], v[94:95], v[212:213]
	v_pk_add_f32 v[214:215], v[88:89], v[214:215]
	v_pk_add_f32 v[216:217], v[90:91], v[216:217]
	v_cvt_pk_bf16_f32 v88, v210, v211
	v_cvt_pk_bf16_f32 v89, v212, v213
	v_cvt_pk_bf16_f32 v90, v214, v215
	v_cvt_pk_bf16_f32 v91, v216, v217
	global_store_dwordx4 v[254:255], v[88:91], off
	global_load_dwordx4 v[210:213], v[168:169], off offset:512
	global_load_dwordx4 v[214:217], v[168:169], off offset:528
	s_waitcnt vmcnt(21)
	v_pk_add_f32 v[218:219], v[84:85], v[218:219]
	v_pk_add_f32 v[220:221], v[86:87], v[220:221]
	v_pk_add_f32 v[222:223], v[80:81], v[222:223]
	v_pk_add_f32 v[224:225], v[82:83], v[224:225]
	v_cvt_pk_bf16_f32 v80, v218, v219
	v_cvt_pk_bf16_f32 v81, v220, v221
	v_cvt_pk_bf16_f32 v82, v222, v223
	v_cvt_pk_bf16_f32 v83, v224, v225
	global_store_dwordx4 v[254:255], v[80:83], off offset:256
	global_load_dwordx4 v[218:221], v[170:171], off
	global_load_dwordx4 v[222:225], v[170:171], off offset:16
	v_add_u32_e32 v254, 0x30, v144
	v_ashrrev_i32_e32 v255, 31, v254
	v_lshlrev_b64 v[254:255], 11, v[254:255]
	v_lshl_add_u64 v[254:255], s[20:21], 0, v[254:255]
	v_lshl_add_u64 v[254:255], v[254:255], 0, v[146:147]
	s_waitcnt vmcnt(22)
	v_pk_add_f32 v[228:229], v[76:77], v[228:229]
	v_pk_add_f32 v[230:231], v[78:79], v[230:231]
	v_pk_add_f32 v[232:233], v[72:73], v[232:233]
	v_pk_add_f32 v[234:235], v[74:75], v[234:235]
	v_cvt_pk_bf16_f32 v72, v228, v229
	v_cvt_pk_bf16_f32 v73, v230, v231
	v_cvt_pk_bf16_f32 v74, v232, v233
	v_cvt_pk_bf16_f32 v75, v234, v235
	global_store_dwordx4 v[254:255], v[72:75], off
	global_load_dwordx4 v[228:231], v[170:171], off offset:512
	global_load_dwordx4 v[232:235], v[170:171], off offset:528
	s_waitcnt vmcnt(23)
	v_pk_add_f32 v[236:237], v[68:69], v[236:237]
	v_pk_add_f32 v[238:239], v[70:71], v[238:239]
	v_pk_add_f32 v[240:241], v[64:65], v[240:241]
	v_pk_add_f32 v[242:243], v[66:67], v[242:243]
	v_cvt_pk_bf16_f32 v64, v236, v237
	v_cvt_pk_bf16_f32 v65, v238, v239
	v_cvt_pk_bf16_f32 v66, v240, v241
	v_cvt_pk_bf16_f32 v67, v242, v243
	global_store_dwordx4 v[254:255], v[64:67], off offset:256
	v_add_u32_e32 v254, 0x80, v144
	v_ashrrev_i32_e32 v255, 31, v254
	v_lshlrev_b64 v[254:255], 11, v[254:255]
	v_lshl_add_u64 v[254:255], s[20:21], 0, v[254:255]
	v_lshl_add_u64 v[254:255], v[254:255], 0, v[146:147]
	s_waitcnt vmcnt(22)
; __device__ __forceinline__ unsigned cvt_pk_bf16(float lo, float hi) { unsigned r; asm volatile("v_cvt_pk_bf16_f32 %0, %1, %2" : "=v"(r) : "v"(lo), "v"(hi)); return r; }
;     __device__ __forceinline__ void operator()(const f32x4 (&acc)[2][2][4][2], const Unit& u, int wr, int wc, int fr, int fq) const {
;     ...
;         for (int ai = 0; ai < 2; ++ai)
; #pragma unroll
;             for (int m = 0; m < 4; ++m) {
;                 const int row = u.pm * BM + ai * HALF + wr * 64 + m * 16 + fr;
;                 const float* xr = xrow(xp, xs, row);
; #pragma unroll
;                 for (int bj = 0; bj < 2; ++bj) {
;                     const int col = u.pn * BM + bj * HALF + wc * 32 + 8 * fq;
;                     const f32x4 x0 = *(const f32x4*)(xr + col), x1v = *(const f32x4*)(xr + col + 4);
;                     const f32x4 v0 = acc[ai][bj][m][0] + x0, v1 = acc[ai][bj][m][1] + x1v;
;                     u32x4 w; w.x = cvt_pk_bf16(v0[0], v0[1]); w.y = cvt_pk_bf16(v0[2], v0[3]); w.z = cvt_pk_bf16(v1[0], v1[1]); w.w = cvt_pk_bf16(v1[2], v1[3]);
;                     *(u32x4*)(X1B + (size_t)row * D + col) = w;
;                 }
;             }
	v_pk_add_f32 v[244:245], v[60:61], v[244:245]
	v_pk_add_f32 v[246:247], v[62:63], v[246:247]
	v_pk_add_f32 v[248:249], v[56:57], v[248:249]
	v_pk_add_f32 v[250:251], v[58:59], v[250:251]
	v_cvt_pk_bf16_f32 v56, v244, v245
	v_cvt_pk_bf16_f32 v57, v246, v247
	v_cvt_pk_bf16_f32 v58, v248, v249
	v_cvt_pk_bf16_f32 v59, v250, v251
	global_store_dwordx4 v[254:255], v[56:59], off
	s_waitcnt vmcnt(20)
	v_pk_add_f32 v[172:173], v[52:53], v[172:173]
	v_pk_add_f32 v[174:175], v[54:55], v[174:175]
	v_pk_add_f32 v[176:177], v[48:49], v[176:177]
	v_pk_add_f32 v[178:179], v[50:51], v[178:179]
	v_cvt_pk_bf16_f32 v48, v172, v173
	v_cvt_pk_bf16_f32 v49, v174, v175
	v_cvt_pk_bf16_f32 v50, v176, v177
	v_cvt_pk_bf16_f32 v51, v178, v179
	global_store_dwordx4 v[254:255], v[48:51], off offset:256
	v_add_u32_e32 v254, 0x90, v144
	v_ashrrev_i32_e32 v255, 31, v254
	v_lshlrev_b64 v[254:255], 11, v[254:255]
	v_lshl_add_u64 v[254:255], s[20:21], 0, v[254:255]
	v_lshl_add_u64 v[254:255], v[254:255], 0, v[146:147]
	s_waitcnt vmcnt(18)
	v_pk_add_f32 v[182:183], v[44:45], v[182:183]
	v_pk_add_f32 v[184:185], v[46:47], v[184:185]
	v_pk_add_f32 v[186:187], v[40:41], v[186:187]
	v_pk_add_f32 v[188:189], v[42:43], v[188:189]
	v_cvt_pk_bf16_f32 v40, v182, v183
	v_cvt_pk_bf16_f32 v41, v184, v185
	v_cvt_pk_bf16_f32 v42, v186, v187
	v_cvt_pk_bf16_f32 v43, v188, v189
	global_store_dwordx4 v[254:255], v[40:43], off
	s_waitcnt vmcnt(16)
	v_pk_add_f32 v[194:195], v[36:37], v[194:195]
	v_pk_add_f32 v[196:197], v[38:39], v[196:197]
	v_pk_add_f32 v[198:199], v[32:33], v[198:199]
	v_pk_add_f32 v[200:201], v[34:35], v[200:201]
	v_cvt_pk_bf16_f32 v32, v194, v195
	v_cvt_pk_bf16_f32 v33, v196, v197
	v_cvt_pk_bf16_f32 v34, v198, v199
	v_cvt_pk_bf16_f32 v35, v200, v201
	global_store_dwordx4 v[254:255], v[32:35], off offset:256
	v_add_u32_e32 v254, 0xa0, v144
	v_ashrrev_i32_e32 v255, 31, v254
	v_lshlrev_b64 v[254:255], 11, v[254:255]
	v_lshl_add_u64 v[254:255], s[20:21], 0, v[254:255]
	v_lshl_add_u64 v[254:255], v[254:255], 0, v[146:147]
	s_waitcnt vmcnt(14)
	v_pk_add_f32 v[202:203], v[28:29], v[202:203]
	v_pk_add_f32 v[204:205], v[30:31], v[204:205]
	v_pk_add_f32 v[206:207], v[24:25], v[206:207]
	v_pk_add_f32 v[208:209], v[26:27], v[208:209]
	v_cvt_pk_bf16_f32 v24, v202, v203
	v_cvt_pk_bf16_f32 v25, v204, v205
	v_cvt_pk_bf16_f32 v26, v206, v207
	v_cvt_pk_bf16_f32 v27, v208, v209
	global_store_dwordx4 v[254:255], v[24:27], off
	s_waitcnt vmcnt(12)
	v_pk_add_f32 v[210:211], v[20:21], v[210:211]
	v_pk_add_f32 v[212:213], v[22:23], v[212:213]
	v_pk_add_f32 v[214:215], v[16:17], v[214:215]
	v_pk_add_f32 v[216:217], v[18:19], v[216:217]
	v_cvt_pk_bf16_f32 v16, v210, v211
	v_cvt_pk_bf16_f32 v17, v212, v213
	v_cvt_pk_bf16_f32 v18, v214, v215
	v_cvt_pk_bf16_f32 v19, v216, v217
	global_store_dwordx4 v[254:255], v[16:19], off offset:256
	v_add_u32_e32 v254, 0xb0, v144
	v_ashrrev_i32_e32 v255, 31, v254
	v_lshlrev_b64 v[254:255], 11, v[254:255]
	v_lshl_add_u64 v[254:255], s[20:21], 0, v[254:255]
	v_lshl_add_u64 v[254:255], v[254:255], 0, v[146:147]
	s_waitcnt vmcnt(10)
	v_pk_add_f32 v[218:219], v[12:13], v[218:219]
	v_pk_add_f32 v[220:221], v[14:15], v[220:221]
	v_pk_add_f32 v[222:223], v[8:9], v[222:223]
	v_pk_add_f32 v[224:225], v[10:11], v[224:225]
	v_cvt_pk_bf16_f32 v8, v218, v219
	v_cvt_pk_bf16_f32 v9, v220, v221
	v_cvt_pk_bf16_f32 v10, v222, v223
	v_cvt_pk_bf16_f32 v11, v224, v225
	global_store_dwordx4 v[254:255], v[8:11], off
	s_waitcnt vmcnt(8)
	v_pk_add_f32 v[228:229], v[4:5], v[228:229]
	v_pk_add_f32 v[230:231], v[6:7], v[230:231]
	v_pk_add_f32 v[232:233], v[0:1], v[232:233]
	v_pk_add_f32 v[234:235], v[2:3], v[234:235]
	v_cvt_pk_bf16_f32 v0, v228, v229
	v_cvt_pk_bf16_f32 v1, v230, v231
	v_cvt_pk_bf16_f32 v2, v232, v233
	v_cvt_pk_bf16_f32 v3, v234, v235
	global_store_dwordx4 v[254:255], v[0:3], off offset:256
	s_andn2_b64 vcc, exec, s[0:1]
	s_mov_b64 s[0:1], -1
	s_cbranch_vccnz .LBB0_509
	s_andn2_b64 vcc, exec, s[4:5]
	s_cbranch_vccnz .LBB0_508
	s_barrier
	s_branch .LBB0_508

; #define LAS __attribute__((address_space(3)))
; __global__ void __launch_bounds__(NWAVES * 64, 2) mk_fwd(Params P) {
;     ...
;     if (IN(5)) {
;         const int gw = vcu * NWAVES + wave, NGW = G * NWAVES;
;         const unsigned long long ub_ = (unsigned long long)(uintptr_t)U8, vb_ = (unsigned long long)(uintptr_t)V8;
;         const unsigned long long ubu_ = ((unsigned long long)(unsigned)__builtin_amdgcn_readfirstlane((int)(ub_ >> 32)) << 32) | (unsigned)__builtin_amdgcn_readfirstlane((int)ub_);
;         const unsigned long long vbu_ = ((unsigned long long)(unsigned)__builtin_amdgcn_readfirstlane((int)(vb_ >> 32)) << 32) | (unsigned)__builtin_amdgcn_readfirstlane((int)vb_);
;         const __amdgpu_buffer_rsrc_t U6r = __builtin_amdgcn_make_buffer_rsrc((void*)(uintptr_t)ubu_, 0, NEXP * 1024, 0x00020000), V6r = __builtin_amdgcn_make_buffer_rsrc((void*)(uintptr_t)vbu_, 0, NEXP * 768, 0x00020000);
;         pw_ptr L = (pw_ptr)((LAS char*)lds + wave * PW_BYTES);
;         for (int tok0 = gw * PT; tok0 < M; tok0 += NGW * PT) peer_block(tok0, P.out, X1B, TKI, TKS, U6r, V6r, USC, VSC, P.finw, L, lane);
.LBB0_675:
	s_cmp_lt_i32 s72, 6
	s_cselect_b64 s[0:1], -1, 0
	s_cmp_gt_i32 s73, 5
	s_cselect_b64 s[2:3], -1, 0
	s_and_b64 s[0:1], s[0:1], s[2:3]
	s_andn2_b64 vcc, exec, s[0:1]
	s_cbranch_vccnz .LBB0_745
	v_readlane_b32 s76, v252, 2
	v_readlane_b32 s77, v252, 3
	v_readlane_b32 s78, v252, 4
	v_readlane_b32 s84, v252, 9
	s_nop 3
	s_lshl_b32 s78, s78, 8
	s_add_i32 s78, s78, 0x3800
	s_add_u32 s76, s76, s78
	s_addc_u32 s77, s77, 0
	v_mov_b32_e32 v136, 0x25ff0
	ds_read_b32 v137, v136
	s_waitcnt lgkmcnt(0)
	v_readfirstlane_b32 s78, v137
	s_mov_b32 s79, 0
	v_readlane_b32 s0, v252, 0
	s_lshl_b32 s0, s0, 3
	v_readlane_b32 s1, v252, 9
	s_add_i32 s0, s0, s1
	s_cmpk_gt_i32 s0, 0x1fff
	s_cbranch_scc1 .LBB0_745
	v_mov_b32_e32 v73, 0
	v_lshlrev_b32_e32 v4, 5, v193
	v_mov_b32_e32 v5, v73
	v_lshl_add_u64 v[76:77], s[20:21], 0, v[4:5]
	v_mbcnt_lo_u32_b32 v4, -1, 0
	v_mbcnt_hi_u32_b32 v4, -1, v4
	v_and_b32_e32 v9, 64, v4
	v_xor_b32_e32 v5, 16, v4
	v_add_u32_e32 v9, 64, v9
	v_cmp_lt_i32_e32 vcc, v5, v9
	v_lshlrev_b32_e32 v0, 1, v180
	v_and_b32_e32 v7, 0x70, v0
	v_cndmask_b32_e32 v5, v4, v5, vcc
	v_lshlrev_b32_e32 v88, 2, v5
	v_xor_b32_e32 v5, 32, v4
	v_lshrrev_b32_e32 v0, 4, v193
	v_cmp_lt_i32_e32 vcc, v5, v9
	v_mul_u32_u24_e32 v72, 0xc000, v0
	v_and_b32_e32 v0, 15, v180
	v_cndmask_b32_e32 v4, v4, v5, vcc
	v_lshlrev_b32_e32 v0, 2, v0
	v_mov_b32_e32 v1, v73
	v_lshlrev_b32_e32 v89, 2, v4
	v_and_b32_e32 v4, 2, v180
	v_and_b32_e32 v6, 7, v180
	v_lshl_add_u64 v[74:75], s[6:7], 0, v[0:1]
	v_cmp_eq_u32_e64 s[4:5], 0, v4
	v_and_b32_e32 v4, 1, v180
	v_lshl_add_u64 v[78:79], s[8:9], 0, v[0:1]
	v_mov_b32_e32 v0, 0x200000
	v_readlane_b32 s1, v252, 9
	v_lshlrev_b32_e32 v5, 3, v4
	v_bfe_u32 v9, v180, 1, 2
	v_lshl_or_b32 v92, v6, 3, v0
	v_and_b32_e32 v0, 8, v180
	s_mulk_i32 s1, 0x4840
	v_lshlrev_b32_e32 v2, 4, v193
	v_mov_b32_e32 v3, v73
	v_or3_b32 v10, v5, v9, v7
	v_cmp_eq_u32_e64 s[8:9], 0, v0
	v_and_b32_e32 v0, 56, v180
	s_mov_b32 s63, 0x20000
	s_add_i32 s33, s1, 0
	v_lshlrev_b32_e32 v8, 2, v193
	v_lshlrev_b32_e32 v90, 4, v6
	v_lshlrev_b32_e32 v91, 2, v7
	v_lshlrev_b32_e32 v10, 2, v10
	v_lshl_add_u64 v[80:81], s[56:57], 0, v[2:3]
	v_lshlrev_b32_e32 v82, 3, v193
	v_mov_b32_e32 v83, v73
	v_lshl_add_u64 v[86:87], s[54:55], 0, v[2:3]
	v_or3_b32 v1, v9, v7, v5
	v_mov_b32_e32 v3, 0xc00
	v_lshl_or_b32 v0, v6, 6, v0
	s_mov_b32 s62, 0x1000000
	s_and_b32 s61, s61, 0xffff
	s_mov_b32 s66, 0xc00000
	s_mov_b32 s67, s63
	s_and_b32 s65, s65, 0xffff
	s_mul_i32 s12, s0, 6
	s_waitcnt lgkmcnt(0)
	s_mov_b32 s42, 64
	v_cmp_eq_u32_e64 s[0:1], 0, v193
	v_cmp_gt_u32_e64 s[2:3], 4, v6
	v_cmp_eq_u32_e64 s[6:7], 0, v4
	v_lshl_add_u64 v[84:85], s[20:21], 0, v[82:83]
	s_mul_i32 s43, s90, 48
	v_or_b32_e32 v83, 0x200, v91
	v_lshl_or_b32 v93, v1, 2, v3
	v_add_u32_e32 v94, 0x1840, v90
	v_add_u32_e32 v95, 0x1840, v0
	v_add_u32_e32 v96, s33, v8
	s_mov_b32 s44, 0xda24260
	s_mov_b32 s45, 0x42fe0000
	s_mov_b32 s46, 0x40c0c00
	v_add_u32_e32 v97, s33, v2
	v_mov_b32_e32 v98, 0x358637bd
	s_mov_b32 s47, 0xf800000
	v_mov_b32_e32 v99, 0x260
	s_movk_i32 s48, 0x80
	s_mov_b32 s49, 0xe00000
	v_add_u32_e32 v100, s33, v10
	s_mov_b32 s50, 0x378e98ab
	s_mov_b32 s51, 0x3b7cd369
	s_mov_b32 s52, 0xbcc618b2
	s_mov_b32 s53, 0x3dda74e4
	s_mov_b32 s54, 0x3f228afd
	s_mov_b32 s55, 0x3e03c728
	s_mov_b32 s56, 0xbfb8aa3b
	s_mov_b32 s57, 0x42ce8ed0
	s_mov_b32 s58, 0xc2b17218
	v_mov_b32_e32 v101, 0x3ba10414
	s_brev_b32 s59, -2
	v_mov_b32_e32 v102, 0xb9c68948
	v_mov_b32_e32 v103, 0x7f800000
	s_branch .LBB0_679

; __device__ __forceinline__ float row16_max(float v) { v = fmaxf(v, dppf<0xB1>(v)); v = fmaxf(v, dppf<0x4E>(v)); v = fmaxf(v, dppf<0x141>(v)); v = fmaxf(v, dppf<0x140>(v)); return v; }
; #define LAS __attribute__((address_space(3)))
; __device__ __forceinline__ void peer_block(int tok0, float* X1, const unsigned short* X1B, const int* TKI, const float* TKS, __amdgpu_buffer_rsrc_t U8r, __amdgpu_buffer_rsrc_t V6, const float* USC, const float* VSC,
;                                            const float* finw, pw_ptr L, int lane) {
;     ...
;     for (int t = 0; t < PT; ++t) {
;         const size_t tk = (size_t)(tok0 + t);
;         const size_t rk0 = ((size_t)(lane >> 4) * M + tk) * 16 + (lane & 15), rk1 = rk0 + (size_t)4 * M * 16;
;         *(LAS int*)(L + PW_REC + t * 512 + lane * 4) = TKI[rk0]; *(LAS int*)(L + PW_REC + t * 512 + 256 + lane * 4) = TKI[rk1];
;         *(LAS int*)(L + PW_ACT + t * 512 + lane * 4) = 0; *(LAS int*)(L + PW_ACT + t * 512 + 256 + lane * 4) = 0;
;         const v4u* xb = (const v4u*)(X1B + tk * D + 16 * lane); float ss = 0.f, am = 0.f; float xv[16];
;         const v4u xb0 = xb[0], xb1 = xb[1];
; #pragma unroll
;         for (int q = 0; q < 4; ++q) { const unsigned w0 = (q < 2) ? xb0[2 * (q & 1)] : xb1[2 * (q & 1)], w1 = (q < 2) ? xb0[2 * (q & 1) + 1] : xb1[2 * (q & 1) + 1];
;             const f32x4 a = {__uint_as_float(w0 << 16), __uint_as_float(w0 & 0xffff0000u), __uint_as_float(w1 << 16), __uint_as_float(w1 & 0xffff0000u)};
;             ss += a[0] * a[0] + a[1] * a[1] + a[2] * a[2] + a[3] * a[3];
;             am = fmaxf(am, fmaxf(fmaxf(fabsf(a[0]), fabsf(a[1])), fmaxf(fabsf(a[2]), fabsf(a[3])))); xv[4 * q] = a[0]; xv[4 * q + 1] = a[1]; xv[4 * q + 2] = a[2]; xv[4 * q + 3] = a[3]; }
;         am = row16_max(am); am = fmaxf(am, __shfl_xor(am, 16)); am = fmaxf(am, __shfl_xor(am, 32)); am = fmaxf(am, 1e-30f);
;         const float qs = 127.0f / am; v4u xq;
; #pragma unroll
;         for (int q = 0; q < 4; ++q) { unsigned w = 0u;
; #pragma unroll
;             for (int j = 0; j < 4; ++j) w |= ((unsigned)(int)rintf(xv[4 * q + j] * qs) & 0xffu) << (8 * j);
;             xq[q] = w; }
;         *(LAS v4u*)(L + PW_Y + t * 1024 + 16 * lane) = xq;
.LBB0_679:
	s_add_i32 s79, s79, 1
	s_cmp_lg_u32 s84, 0
	s_cbranch_scc1 .Lxs_wait_blk
	s_mul_i32 s80, s78, s79
	v_mov_b32_e32 v138, 0
	v_mov_b32_e32 v139, 1
	s_mov_b64 s[82:83], exec
	s_mov_b64 exec, 1
	global_atomic_add v138, v139, s[76:77]
	s_movk_i32 s81, 0
.Lxs_poll_blk:
	global_load_dword v139, v138, s[76:77] sc1
	s_waitcnt vmcnt(0)
	v_cmp_le_u32_e32 vcc, s80, v139
	s_nop 1
	s_cmp_lg_u64 vcc, 0
	s_cbranch_scc1 .Lxs_got_blk
	s_sleep 1
	s_addk_i32 s81, 1
	s_cmpk_lt_i32 s81, 0x2000
	s_cbranch_scc1 .Lxs_poll_blk
.Lxs_got_blk:
	s_mov_b64 exec, s[82:83]
.Lxs_wait_blk:
	s_barrier
	s_ashr_i32 s13, s12, 31
	s_lshl_b64 s[18:19], s[12:13], 11
	v_lshl_add_u64 v[4:5], s[12:13], 0, v[72:73]
	v_lshl_add_u64 v[8:9], v[76:77], 0, s[18:19]
	v_lshlrev_b64 v[40:41], 6, v[4:5]
	global_load_dwordx4 v[0:3], v[8:9], off offset:16
	v_lshl_add_u64 v[10:11], v[74:75], 0, v[40:41]
	v_add_co_u32_e32 v12, vcc, 0xc00000, v10
	s_waitcnt vmcnt(0)
	v_and_b32_e32 v16, 0xffff0000, v3
	v_addc_co_u32_e32 v13, vcc, 0, v11, vcc
	global_load_dword v14, v[10:11], off
	global_load_dword v15, v[12:13], off
	global_load_dwordx4 v[4:7], v[8:9], off
	v_lshlrev_b32_e32 v10, 16, v1
	v_and_b32_e32 v1, 0xffff0000, v1
	v_lshlrev_b32_e32 v13, 16, v3
	v_lshlrev_b32_e32 v8, 16, v0
	v_and_b32_e32 v9, 0xffff0000, v0
	v_max_f32_e64 v0, |v1|, |v1|
	v_max_f32_e64 v3, |v10|, |v10|
	v_max_f32_e64 v18, |v16|, |v16|
	v_max_f32_e64 v19, |v13|, |v13|
	v_max_f32_e32 v0, v3, v0
	v_max_f32_e32 v3, v19, v18
	v_lshlrev_b32_e32 v11, 16, v2
	v_and_b32_e32 v12, 0xffff0000, v2
	v_max3_f32 v0, |v8|, |v9|, v0
	v_max3_f32 v3, |v11|, |v12|, v3
	v_mul_f32_e32 v2, v9, v9
	v_fmac_f32_e32 v2, v8, v8
	v_fmac_f32_e32 v2, v10, v10
	v_fmac_f32_e32 v2, v1, v1
	v_mul_f32_e32 v17, v12, v12
	v_fmac_f32_e32 v17, v11, v11
	v_fmac_f32_e32 v17, v13, v13
	v_fmac_f32_e32 v17, v16, v16
	ds_write2st64_b32 v96, v73, v73 offset0:12 offset1:13
	s_waitcnt vmcnt(1)
	ds_write2st64_b32 v96, v14, v15 offset1:1
	s_waitcnt vmcnt(0)
	v_lshlrev_b32_e32 v15, 16, v5
	v_and_b32_e32 v5, 0xffff0000, v5
	v_lshlrev_b32_e32 v19, 16, v7
	v_and_b32_e32 v7, 0xffff0000, v7
	v_max_f32_e64 v21, |v5|, |v5|
	v_max_f32_e64 v22, |v15|, |v15|
	v_max_f32_e64 v24, |v7|, |v7|
	v_max_f32_e64 v25, |v19|, |v19|
	v_lshlrev_b32_e32 v14, 16, v4
	v_and_b32_e32 v4, 0xffff0000, v4
	v_lshlrev_b32_e32 v18, 16, v6
	v_and_b32_e32 v6, 0xffff0000, v6
	v_max_f32_e32 v21, v22, v21
	v_max_f32_e32 v22, v25, v24
	v_max3_f32 v21, |v14|, |v4|, v21
	v_max3_f32 v22, |v18|, |v6|, v22
	v_max3_f32 v21, v21, 0, v22
	v_max3_f32 v0, v21, v0, v3
	v_mul_f32_e32 v20, v4, v4
	v_mul_f32_e32 v23, v6, v6
	v_mov_b32_dpp v3, v0 quad_perm:[1,0,3,2] row_mask:0xf bank_mask:0xf bound_ctrl:1
	v_max_f32_e32 v3, v3, v3
	v_max_f32_e32 v0, v0, v3
	v_fmac_f32_e32 v20, v14, v14
	v_fmac_f32_e32 v23, v18, v18
	v_mov_b32_dpp v3, v0 quad_perm:[2,3,0,1] row_mask:0xf bank_mask:0xf bound_ctrl:1
	v_max_f32_e32 v3, v3, v3
	v_max_f32_e32 v0, v0, v3
	v_fmac_f32_e32 v20, v15, v15
	v_fmac_f32_e32 v23, v19, v19
	v_mov_b32_dpp v3, v0 row_half_mirror row_mask:0xf bank_mask:0xf bound_ctrl:1
	v_max_f32_e32 v3, v3, v3
	v_max_f32_e32 v0, v0, v3
	v_fmac_f32_e32 v20, v5, v5
	v_fmac_f32_e32 v23, v7, v7
	v_mov_b32_dpp v3, v0 row_mirror row_mask:0xf bank_mask:0xf bound_ctrl:1
	v_max_f32_e32 v3, v3, v3
	v_max_f32_e32 v0, v0, v3
	ds_bpermute_b32 v3, v88, v0
	v_add_f32_e32 v20, v20, v23
	v_add_f32_e32 v20, v20, v2
	s_waitcnt lgkmcnt(0)
	v_max_f32_e32 v3, v3, v3
	v_max_f32_e32 v0, v0, v3
	ds_bpermute_b32 v3, v89, v0
	s_waitcnt lgkmcnt(0)
	v_max3_f32 v0, v0, v3, s44
	v_div_scale_f32 v3, s[10:11], v0, v0, s45
	v_rcp_f32_e32 v21, v3
	v_div_scale_f32 v2, vcc, s45, v0, s45
	v_fma_f32 v22, -v3, v21, 1.0
	v_fmac_f32_e32 v21, v22, v21
	v_mul_f32_e32 v22, v2, v21
	v_fma_f32 v23, -v3, v22, v2
	v_fmac_f32_e32 v22, v23, v21
	v_fma_f32 v2, -v3, v22, v2
	v_div_fmas_f32 v2, v2, v21, v22
	v_div_fixup_f32 v21, v2, v0, s45
	v_mul_f32_e32 v2, v21, v14
	v_mul_f32_e32 v3, v21, v4
	v_mul_f32_e32 v5, v21, v5
	v_mul_f32_e32 v6, v21, v6
	v_mul_f32_e32 v4, v21, v15
	v_mul_f32_e32 v14, v21, v18
	v_mul_f32_e32 v15, v21, v19
	v_mul_f32_e32 v7, v21, v7
	v_rndne_f32_e32 v2, v2
	v_rndne_f32_e32 v3, v3
	v_rndne_f32_e32 v5, v5
	v_rndne_f32_e32 v6, v6
	v_rndne_f32_e32 v4, v4
	v_rndne_f32_e32 v14, v14
	v_rndne_f32_e32 v15, v15
	v_rndne_f32_e32 v7, v7
	v_cvt_i32_f32_e32 v2, v2
	v_cvt_i32_f32_e32 v3, v3
	v_cvt_i32_f32_e32 v5, v5
	v_cvt_i32_f32_e32 v6, v6
	v_cvt_i32_f32_sdwa v4, v4 dst_sel:WORD_1 dst_unused:UNUSED_PAD src0_sel:DWORD
	v_cvt_i32_f32_e32 v14, v14
	v_cvt_i32_f32_sdwa v15, v15 dst_sel:WORD_1 dst_unused:UNUSED_PAD src0_sel:DWORD
	v_cvt_i32_f32_e32 v7, v7
	v_lshlrev_b32_e32 v3, 8, v3
	v_perm_b32 v2, v5, v2, s46
	v_lshlrev_b32_e32 v5, 8, v6
	v_mul_f32_e32 v9, v21, v9
	v_and_b32_e32 v4, 0xff0000, v4
	v_and_b32_e32 v6, 0xff0000, v15
	v_perm_b32 v7, v7, v14, s46
	v_and_b32_e32 v3, 0xff00, v3
	v_and_b32_e32 v5, 0xff00, v5
	v_mul_f32_e32 v8, v21, v8
	v_rndne_f32_e32 v9, v9
	v_or3_b32 v2, v2, v3, v4
	v_or3_b32 v3, v7, v5, v6
	v_mul_f32_e32 v5, v21, v10
	v_mul_f32_e32 v1, v21, v1
	v_rndne_f32_e32 v8, v8
	v_cvt_i32_f32_e32 v4, v9
	v_rndne_f32_e32 v5, v5
	v_rndne_f32_e32 v1, v1
	v_cvt_i32_f32_e32 v8, v8
	v_cvt_i32_f32_sdwa v5, v5 dst_sel:WORD_1 dst_unused:UNUSED_PAD src0_sel:DWORD
	v_cvt_i32_f32_e32 v1, v1
	v_lshlrev_b32_e32 v4, 8, v4
	v_and_b32_e32 v4, 0xff00, v4
	v_and_b32_e32 v5, 0xff0000, v5
	v_perm_b32 v1, v1, v8, s46
	v_or3_b32 v4, v1, v4, v5
	v_mul_f32_e32 v5, v21, v12
	v_mul_f32_e32 v1, v21, v11
	v_rndne_f32_e32 v5, v5
	v_mul_f32_e32 v6, v21, v13
	v_mul_f32_e32 v7, v21, v16
	v_rndne_f32_e32 v1, v1
	v_cvt_i32_f32_e32 v5, v5
	v_rndne_f32_e32 v6, v6
	v_rndne_f32_e32 v7, v7
	v_cvt_i32_f32_e32 v1, v1
	v_cvt_i32_f32_sdwa v6, v6 dst_sel:WORD_1 dst_unused:UNUSED_PAD src0_sel:DWORD
	v_cvt_i32_f32_e32 v7, v7
	v_lshlrev_b32_e32 v5, 8, v5
	v_and_b32_e32 v5, 0xff00, v5
	v_and_b32_e32 v6, 0xff0000, v6
	v_perm_b32 v1, v7, v1, s46
	v_or3_b32 v5, v1, v5, v6
	v_add_f32_e32 v1, v17, v20
	ds_write_b128 v97, v[2:5] offset:6208
	s_nop 0
	v_add_f32_dpp v1, v1, v1 quad_perm:[1,0,3,2] row_mask:0xf bank_mask:0xf bound_ctrl:1
	s_nop 1
	v_add_f32_dpp v1, v1, v1 quad_perm:[2,3,0,1] row_mask:0xf bank_mask:0xf bound_ctrl:1
	s_nop 1
	v_add_f32_dpp v1, v1, v1 row_half_mirror row_mask:0xf bank_mask:0xf bound_ctrl:1
	s_nop 1
	v_add_f32_dpp v1, v1, v1 row_mirror row_mask:0xf bank_mask:0xf bound_ctrl:1
	v_mov_b32_e32 v2, v1
	s_nop 1
	v_permlane16_swap_b32_e32 v1, v2
	v_add_f32_e32 v1, v1, v2
	v_mov_b32_e32 v2, v1
	s_nop 1
	v_permlane32_swap_b32_e32 v1, v2
	s_and_saveexec_b64 s[14:15], s[0:1]
	s_cbranch_execz .LBB0_681
; __device__ __forceinline__ float wave_sum(float v) { v = row16_sum(v); v = swap_add16(v, v); return swap_add32(v, v); }
; #define LAS __attribute__((address_space(3)))
; __device__ __forceinline__ void peer_block(int tok0, float* X1, const unsigned short* X1B, const int* TKI, const float* TKS, __amdgpu_buffer_rsrc_t U8r, __amdgpu_buffer_rsrc_t V6, const float* USC, const float* VSC,
;                                            const float* finw, pw_ptr L, int lane) {
;     ...
;         const float r = 1.0f / sqrtf(wave_sum(ss) * (1.0f / D) + EPS);
;         if (lane == 0) { *(LAS float*)(L + PW_R + t * 8) = r; *(LAS float*)(L + PW_R + t * 8 + 4) = r * am * (1.0f / 127.0f); }
	v_add_f32_e32 v1, v1, v2
	v_fmamk_f32 v1, v1, 0x3a800000, v98
	v_mul_f32_e32 v2, 0x4f800000, v1
	v_cmp_gt_f32_e32 vcc, s47, v1
	s_nop 1
	v_cndmask_b32_e32 v1, v1, v2, vcc
	v_sqrt_f32_e32 v2, v1
	s_nop 0
	v_add_u32_e32 v3, -1, v2
	v_fma_f32 v5, -v3, v2, v1
	v_add_u32_e32 v4, 1, v2
	v_cmp_ge_f32_e64 s[10:11], 0, v5
	s_nop 1
	v_cndmask_b32_e64 v3, v2, v3, s[10:11]
	v_fma_f32 v2, -v4, v2, v1
	v_cmp_lt_f32_e64 s[10:11], 0, v2
	s_nop 1
	v_cndmask_b32_e64 v2, v3, v4, s[10:11]
	v_mul_f32_e32 v3, 0x37800000, v2
	v_cndmask_b32_e32 v2, v2, v3, vcc
	v_cmp_class_f32_e32 vcc, v1, v99
	s_nop 1
	v_cndmask_b32_e32 v1, v2, v1, vcc
	v_div_scale_f32 v2, s[10:11], v1, v1, 1.0
	v_rcp_f32_e32 v3, v2
	s_nop 0
	v_fma_f32 v4, -v2, v3, 1.0
	v_fmac_f32_e32 v3, v4, v3
	v_div_scale_f32 v4, vcc, 1.0, v1, 1.0
	v_mul_f32_e32 v5, v4, v3
	v_fma_f32 v6, -v2, v5, v4
	v_fmac_f32_e32 v5, v6, v3
	v_fma_f32 v2, -v2, v5, v4
	v_div_fmas_f32 v2, v2, v3, v5
	v_div_fixup_f32 v2, v2, v1, 1.0
	v_mul_f32_e32 v0, v0, v2
	v_mul_f32_e32 v3, 0x3c010204, v0
	v_mov_b32_e32 v0, s33
	ds_write_b64 v0, v[2:3] offset:6144

; #define LAS __attribute__((address_space(3)))
; #define PB_RECS(rv, t, q) do { rv = *(const LAS recv_t*)(L + PW_REC + (t) * 512 + (g16 + NPB * (q)) * 4); } while (0)
; template <int CTRL> __device__ __forceinline__ int dppi(int v) { return __builtin_amdgcn_update_dpp(0, v, CTRL, 0xF, 0xF, true); }
; __device__ __forceinline__ int pb_u_part(const v4u (&buf)[4], const v4u& xq, int m) {
;     int d[4];
; #pragma unroll
;     for (int i = 0; i < 4; ++i) { int a = __builtin_amdgcn_sdot4((int)buf[i][0], (int)xq[0], 0, false); a = __builtin_amdgcn_sdot4((int)buf[i][1], (int)xq[1], a, false);
;         a = __builtin_amdgcn_sdot4((int)buf[i][2], (int)xq[2], a, false); d[i] = __builtin_amdgcn_sdot4((int)buf[i][3], (int)xq[3], a, false); }
;     const bool b2 = (m & 4) != 0, b1 = (m & 2) != 0;
;     const int e0 = (b2 ? d[2] : d[0]) + dppi<0x141>(b2 ? d[0] : d[2]), e1 = (b2 ? d[3] : d[1]) + dppi<0x141>(b2 ? d[1] : d[3]);
;     const int f0 = (b1 ? e1 : e0) + dppi<0x4E>(b1 ? e0 : e1);
;     return f0 + dppi<0xB1>(f0);
; }
; __device__ __forceinline__ void peer_block(int tok0, float* X1, const unsigned short* X1B, const int* TKI, const float* TKS, __amdgpu_buffer_rsrc_t U8r, __amdgpu_buffer_rsrc_t V6, const float* USC, const float* VSC,
;                                            const float* finw, pw_ptr L, int lane) {
;     ...
;         for (int it = 0; it < NSU * PT; ++it) {
;             const int c = it / PT, t = it - c * PT; const int soff = c * SLU;
;             const int itn = it + 1, cn = itn / PT, tn = itn - cn * PT;
;             int rq[4];
;             xq = *(const LAS v4u*)(L + PW_Y + t * 1024 + 128 * c + 16 * m);
; #pragma unroll
;             for (int q = 0; q < 4; ++q) {
;                 const int qa = q + NBU - 1;
;                 if (qa < 4) { PB_RECS(rv, t, qa); PB_LOADU(bu[qa % NBU], U8r, rv, soff); }
;                 else if (itn < NSU * PT) { PB_RECS(rv, tn, qa - 4); PB_LOADU(bu[qa % NBU], U8r, rv, cn * SLU); }
;                 rq[q] = pb_u_part(bu[q % NBU], xq, m);
;             }
;             LAS int* ap = (LAS int*)(L + PW_ACT + t * 512 + (g16 + 8 * (m & 1) + (m >> 1)) * 4);
;             ap[0] += (m & 1) ? rq[2] : rq[0]; ap[4] += (m & 1) ? rq[3] : rq[1];
;         }
.LBB0_692:
	s_mul_hi_u32 s68, s11, 0xaaaaaaab
	s_mul_hi_u32 s71, s41, 0xaaaaaaab
	s_lshr_b32 s68, s68, 2
	s_lshr_b32 s71, s71, 2
	s_mul_i32 s72, s71, 6
	s_cmp_eq_u32 s72, s41
	s_cbranch_scc0 .Lpu_nosync
	s_barrier
.Lpu_nosync:
	s_mulk_i32 s68, 0xc00
	s_mul_i32 s74, s71, 0xc00
	s_mulk_i32 s71, 0x1780
	s_add_i32 s69, s33, s10
	s_add_i32 s70, s33, s40
	v_subrev_u32_e32 v16, s68, v83
	v_subrev_u32_e32 v18, s74, v91
	v_subrev_u32_e32 v19, s71, v94
	v_subrev_u32_e32 v17, s74, v93
	v_add_u32_e32 v28, s69, v19
	v_add_u32_e32 v46, s70, v16
	v_add_u32_e32 v24, s70, v18
	v_add_u32_e32 v131, s70, v17
	ds_read_b128 v[16:19], v24 offset:16
	ds_read_b128 v[20:23], v24 offset:32
	ds_read_b128 v[24:27], v24 offset:48
	ds_read_b128 v[28:31], v28
	ds_read_b128 v[46:49], v46
	ds_read2_b32 v[70:71], v131 offset1:4
	s_mul_i32 s72, s11, 0x55800
	s_add_i32 s73, s72, 0x7faa800
	v_mov_b32_e32 v45, 0
	v_mov_b32_e32 v116, 0
	v_mov_b32_e32 v117, 0
	v_mov_b32_e32 v118, 0
	s_and_b32 s73, s73, 0x7e00000
	s_waitcnt lgkmcnt(5)
	v_mad_u32_u16 v16, v16, s48, v90
	v_mad_u32_u16 v50, v17, s48, v90
	v_mad_u32_u16 v51, v18, s48, v90
	v_mad_u32_u16 v52, v19, s48, v90
	s_waitcnt lgkmcnt(3)
	v_mad_u32_u16 v66, v24, s48, v90
	v_mad_u32_u16 v104, v25, s48, v90
	v_mad_u32_u16 v108, v26, s48, v90
	v_mad_u32_u16 v112, v27, s48, v90
	s_waitcnt vmcnt(3) lgkmcnt(2)
	v_dot4c_i32_i8_e32 v45, v12, v28
	s_waitcnt vmcnt(2)
	v_dot4c_i32_i8_e32 v116, v8, v28
	s_waitcnt vmcnt(1)
	v_dot4c_i32_i8_e32 v117, v4, v28
	s_waitcnt vmcnt(0)
	v_dot4c_i32_i8_e32 v118, v0, v28
	v_mad_u32_u16 v0, v20, s48, v90
	v_mad_u32_u16 v4, v21, s48, v90
	v_mad_u32_u16 v8, v22, s48, v90
	v_mad_u32_u16 v12, v23, s48, v90
	s_waitcnt lgkmcnt(1)
	v_mad_u32_u16 v132, v46, s48, v90
	v_mad_u32_u16 v133, v47, s48, v90
	v_mad_u32_u16 v134, v48, s48, v90
	v_mad_u32_u16 v135, v49, s48, v90
	buffer_load_dwordx4 v[16:19], v16, s[60:63], s73 offen
	s_nop 0
	buffer_load_dwordx4 v[20:23], v50, s[60:63], s73 offen
	buffer_load_dwordx4 v[24:27], v51, s[60:63], s73 offen
	buffer_load_dwordx4 v[46:49], v52, s[60:63], s73 offen
	s_nop 0
	buffer_load_dwordx4 v[50:53], v0, s[60:63], s73 offen
	buffer_load_dwordx4 v[54:57], v4, s[60:63], s73 offen
	buffer_load_dwordx4 v[58:61], v8, s[60:63], s73 offen
	buffer_load_dwordx4 v[62:65], v12, s[60:63], s73 offen
	s_nop 0
	buffer_load_dwordx4 v[66:69], v66, s[60:63], s73 offen
	s_nop 0
	buffer_load_dwordx4 v[104:107], v104, s[60:63], s73 offen
	s_nop 0
	buffer_load_dwordx4 v[108:111], v108, s[60:63], s73 offen
	s_nop 0
	buffer_load_dwordx4 v[112:115], v112, s[60:63], s73 offen
	v_dot4c_i32_i8_e32 v45, v13, v29
	v_dot4c_i32_i8_e32 v116, v9, v29
	v_dot4c_i32_i8_e32 v117, v5, v29
	v_dot4c_i32_i8_e32 v118, v1, v29
	s_and_b32 s72, s72, 0x7e00000
	v_dot4c_i32_i8_e32 v45, v14, v30
	v_dot4c_i32_i8_e32 v116, v10, v30
	v_dot4c_i32_i8_e32 v117, v6, v30
	v_dot4c_i32_i8_e32 v118, v2, v30
	v_dot4c_i32_i8_e32 v45, v15, v31
	v_dot4c_i32_i8_e32 v116, v11, v31
	v_dot4c_i32_i8_e32 v117, v7, v31
	v_dot4c_i32_i8_e32 v118, v3, v31
	buffer_load_dwordx4 v[12:15], v132, s[60:63], s72 offen
	buffer_load_dwordx4 v[8:11], v133, s[60:63], s72 offen
	buffer_load_dwordx4 v[4:7], v134, s[60:63], s72 offen
	buffer_load_dwordx4 v[0:3], v135, s[60:63], s72 offen
	v_mov_b32_e32 v119, 0
	v_mov_b32_e32 v120, 0
	v_mov_b32_e32 v121, 0
	v_mov_b32_e32 v122, 0
	v_mov_b32_e32 v123, 0
	v_mov_b32_e32 v124, 0
	v_mov_b32_e32 v125, 0
	v_mov_b32_e32 v126, 0
	v_mov_b32_e32 v127, 0
	v_mov_b32_e32 v128, 0
	v_mov_b32_e32 v129, 0
	v_mov_b32_e32 v130, 0
	v_cndmask_b32_e64 v132, v117, v45, s[2:3]
	v_cndmask_b32_e64 v45, v45, v117, s[2:3]
	v_cndmask_b32_e64 v117, v118, v116, s[2:3]
	v_cndmask_b32_e64 v116, v116, v118, s[2:3]
	v_add_u32_dpp v45, v45, v132 row_half_mirror row_mask:0xf bank_mask:0xf bound_ctrl:1
	s_add_i32 s41, s41, 1
	v_add_u32_dpp v116, v116, v117 row_half_mirror row_mask:0xf bank_mask:0xf bound_ctrl:1
	v_cndmask_b32_e64 v117, v116, v45, s[4:5]
	v_cndmask_b32_e64 v45, v45, v116, s[4:5]
	s_add_i32 s11, s11, 1
	s_addk_i32 s40, 0x200
	v_add_u32_dpp v45, v45, v117 quad_perm:[2,3,0,1] row_mask:0xf bank_mask:0xf bound_ctrl:1
	s_addk_i32 s10, 0x400
	s_cmp_eq_u32 s11, 48
	v_add_u32_dpp v45, v45, v45 quad_perm:[1,0,3,2] row_mask:0xf bank_mask:0xf bound_ctrl:1
	s_waitcnt vmcnt(15)
	v_dot4c_i32_i8_e32 v119, v16, v28
	s_waitcnt vmcnt(14)
	v_dot4c_i32_i8_e32 v120, v20, v28
	s_waitcnt vmcnt(13)
	v_dot4c_i32_i8_e32 v121, v24, v28
	s_waitcnt vmcnt(12)
	v_dot4c_i32_i8_e32 v122, v46, v28
	s_waitcnt vmcnt(11)
	v_dot4c_i32_i8_e32 v123, v50, v28
	s_waitcnt vmcnt(10)
	v_dot4c_i32_i8_e32 v124, v54, v28
	s_waitcnt vmcnt(9)
	v_dot4c_i32_i8_e32 v125, v58, v28
	s_waitcnt vmcnt(8)
	v_dot4c_i32_i8_e32 v126, v62, v28
	s_waitcnt vmcnt(7)
	v_dot4c_i32_i8_e32 v127, v66, v28
	s_waitcnt vmcnt(6)
	v_dot4c_i32_i8_e32 v128, v104, v28
	s_waitcnt vmcnt(5)
	v_dot4c_i32_i8_e32 v129, v108, v28
	s_waitcnt vmcnt(4)
; #define LAS __attribute__((address_space(3)))
; #define PB_RECS(rv, t, q) do { rv = *(const LAS recv_t*)(L + PW_REC + (t) * 512 + (g16 + NPB * (q)) * 4); } while (0)
; template <int CTRL> __device__ __forceinline__ int dppi(int v) { return __builtin_amdgcn_update_dpp(0, v, CTRL, 0xF, 0xF, true); }
; __device__ __forceinline__ int pb_u_part(const v4u (&buf)[4], const v4u& xq, int m) {
;     int d[4];
; #pragma unroll
;     for (int i = 0; i < 4; ++i) { int a = __builtin_amdgcn_sdot4((int)buf[i][0], (int)xq[0], 0, false); a = __builtin_amdgcn_sdot4((int)buf[i][1], (int)xq[1], a, false);
;         a = __builtin_amdgcn_sdot4((int)buf[i][2], (int)xq[2], a, false); d[i] = __builtin_amdgcn_sdot4((int)buf[i][3], (int)xq[3], a, false); }
;     const bool b2 = (m & 4) != 0, b1 = (m & 2) != 0;
;     const int e0 = (b2 ? d[2] : d[0]) + dppi<0x141>(b2 ? d[0] : d[2]), e1 = (b2 ? d[3] : d[1]) + dppi<0x141>(b2 ? d[1] : d[3]);
;     const int f0 = (b1 ? e1 : e0) + dppi<0x4E>(b1 ? e0 : e1);
;     return f0 + dppi<0xB1>(f0);
; }
; __device__ __forceinline__ void peer_block(int tok0, float* X1, const unsigned short* X1B, const int* TKI, const float* TKS, __amdgpu_buffer_rsrc_t U8r, __amdgpu_buffer_rsrc_t V6, const float* USC, const float* VSC,
;                                            const float* finw, pw_ptr L, int lane) {
;     ...
;         for (int it = 0; it < NSU * PT; ++it) {
;             const int c = it / PT, t = it - c * PT; const int soff = c * SLU;
;             const int itn = it + 1, cn = itn / PT, tn = itn - cn * PT;
;             int rq[4];
;             xq = *(const LAS v4u*)(L + PW_Y + t * 1024 + 128 * c + 16 * m);
; #pragma unroll
;             for (int q = 0; q < 4; ++q) {
;                 const int qa = q + NBU - 1;
;                 if (qa < 4) { PB_RECS(rv, t, qa); PB_LOADU(bu[qa % NBU], U8r, rv, soff); }
;                 else if (itn < NSU * PT) { PB_RECS(rv, tn, qa - 4); PB_LOADU(bu[qa % NBU], U8r, rv, cn * SLU); }
;                 rq[q] = pb_u_part(bu[q % NBU], xq, m);
;             }
;             LAS int* ap = (LAS int*)(L + PW_ACT + t * 512 + (g16 + 8 * (m & 1) + (m >> 1)) * 4);
;             ap[0] += (m & 1) ? rq[2] : rq[0]; ap[4] += (m & 1) ? rq[3] : rq[1];
;         }
	v_dot4c_i32_i8_e32 v130, v112, v28
	v_dot4c_i32_i8_e32 v119, v17, v29
	v_dot4c_i32_i8_e32 v120, v21, v29
	v_dot4c_i32_i8_e32 v121, v25, v29
	v_dot4c_i32_i8_e32 v122, v47, v29
	v_dot4c_i32_i8_e32 v123, v51, v29
	v_dot4c_i32_i8_e32 v124, v55, v29
	v_dot4c_i32_i8_e32 v125, v59, v29
	v_dot4c_i32_i8_e32 v126, v63, v29
	v_dot4c_i32_i8_e32 v127, v67, v29
	v_dot4c_i32_i8_e32 v128, v105, v29
	v_dot4c_i32_i8_e32 v129, v109, v29
	v_dot4c_i32_i8_e32 v130, v113, v29
	v_dot4c_i32_i8_e32 v119, v18, v30
	v_dot4c_i32_i8_e32 v120, v22, v30
	v_dot4c_i32_i8_e32 v121, v26, v30
	v_dot4c_i32_i8_e32 v122, v48, v30
	v_dot4c_i32_i8_e32 v123, v52, v30
	v_dot4c_i32_i8_e32 v124, v56, v30
	v_dot4c_i32_i8_e32 v125, v60, v30
	v_dot4c_i32_i8_e32 v126, v64, v30
	v_dot4c_i32_i8_e32 v127, v68, v30
	v_dot4c_i32_i8_e32 v128, v106, v30
	v_dot4c_i32_i8_e32 v129, v110, v30
	v_dot4c_i32_i8_e32 v130, v114, v30
	v_dot4c_i32_i8_e32 v119, v19, v31
	v_dot4c_i32_i8_e32 v120, v23, v31
	v_dot4c_i32_i8_e32 v121, v27, v31
	v_dot4c_i32_i8_e32 v122, v49, v31
	v_dot4c_i32_i8_e32 v123, v53, v31
	v_dot4c_i32_i8_e32 v124, v57, v31
	v_dot4c_i32_i8_e32 v125, v61, v31
	v_dot4c_i32_i8_e32 v126, v65, v31
	v_dot4c_i32_i8_e32 v127, v69, v31
	v_dot4c_i32_i8_e32 v128, v107, v31
	v_dot4c_i32_i8_e32 v129, v111, v31
	v_dot4c_i32_i8_e32 v130, v115, v31
	v_cndmask_b32_e64 v16, v121, v119, s[2:3]
	v_cndmask_b32_e64 v17, v119, v121, s[2:3]
	v_cndmask_b32_e64 v18, v122, v120, s[2:3]
	v_cndmask_b32_e64 v19, v120, v122, s[2:3]
	v_cndmask_b32_e64 v20, v125, v123, s[2:3]
	v_cndmask_b32_e64 v21, v123, v125, s[2:3]
	v_cndmask_b32_e64 v22, v126, v124, s[2:3]
	v_cndmask_b32_e64 v23, v124, v126, s[2:3]
	v_cndmask_b32_e64 v24, v129, v127, s[2:3]
	v_cndmask_b32_e64 v25, v127, v129, s[2:3]
	v_cndmask_b32_e64 v26, v130, v128, s[2:3]
	v_cndmask_b32_e64 v27, v128, v130, s[2:3]
	v_add_u32_dpp v16, v17, v16 row_half_mirror row_mask:0xf bank_mask:0xf bound_ctrl:1
	v_add_u32_dpp v17, v19, v18 row_half_mirror row_mask:0xf bank_mask:0xf bound_ctrl:1
	v_add_u32_dpp v18, v21, v20 row_half_mirror row_mask:0xf bank_mask:0xf bound_ctrl:1
	v_add_u32_dpp v19, v23, v22 row_half_mirror row_mask:0xf bank_mask:0xf bound_ctrl:1
	v_add_u32_dpp v20, v25, v24 row_half_mirror row_mask:0xf bank_mask:0xf bound_ctrl:1
	v_add_u32_dpp v21, v27, v26 row_half_mirror row_mask:0xf bank_mask:0xf bound_ctrl:1
	v_cndmask_b32_e64 v22, v17, v16, s[4:5]
	v_cndmask_b32_e64 v16, v16, v17, s[4:5]
	v_cndmask_b32_e64 v17, v19, v18, s[4:5]
	v_cndmask_b32_e64 v18, v18, v19, s[4:5]
	v_cndmask_b32_e64 v19, v21, v20, s[4:5]
	v_cndmask_b32_e64 v20, v20, v21, s[4:5]
	v_add_u32_dpp v16, v16, v22 quad_perm:[2,3,0,1] row_mask:0xf bank_mask:0xf bound_ctrl:1
	v_add_u32_dpp v17, v18, v17 quad_perm:[2,3,0,1] row_mask:0xf bank_mask:0xf bound_ctrl:1
	v_add_u32_dpp v18, v20, v19 quad_perm:[2,3,0,1] row_mask:0xf bank_mask:0xf bound_ctrl:1
	v_add_u32_dpp v16, v16, v16 quad_perm:[1,0,3,2] row_mask:0xf bank_mask:0xf bound_ctrl:1
	v_add_u32_dpp v17, v17, v17 quad_perm:[1,0,3,2] row_mask:0xf bank_mask:0xf bound_ctrl:1
	v_add_u32_dpp v18, v18, v18 quad_perm:[1,0,3,2] row_mask:0xf bank_mask:0xf bound_ctrl:1
	v_cndmask_b32_e64 v17, v17, v45, s[6:7]
	v_cndmask_b32_e64 v16, v18, v16, s[6:7]
	s_waitcnt lgkmcnt(0)
	v_add_u32_e32 v17, v70, v17
	v_add_u32_e32 v16, v71, v16
	ds_write2_b32 v131, v17, v16 offset1:4
	s_cbranch_scc0 .LBB0_692
	ds_read_b128 v[16:19], v44 offset:2576
	ds_read_b128 v[46:49], v44 offset:2592
	v_add_u32_e32 v45, s33, v90
	v_mov_b32_e32 v119, 0
	v_mov_b32_e32 v116, 0
	s_waitcnt lgkmcnt(1)
	v_mad_u32_u16 v16, v16, s48, v90
	v_mad_u32_u16 v20, v17, s48, v90
	v_mad_u32_u16 v24, v18, s48, v90
	v_mad_u32_u16 v28, v19, s48, v90
	buffer_load_dwordx4 v[16:19], v16, s[60:63], s49 offen
	s_nop 0
	buffer_load_dwordx4 v[20:23], v20, s[60:63], s49 offen
	s_nop 0
	buffer_load_dwordx4 v[24:27], v24, s[60:63], s49 offen
	s_nop 0
	buffer_load_dwordx4 v[28:31], v28, s[60:63], s49 offen
	s_waitcnt lgkmcnt(0)
	v_mad_u32_u16 v46, v46, s48, v90
	buffer_load_dwordx4 v[50:53], v46, s[60:63], s49 offen
	v_mad_u32_u16 v46, v47, s48, v90
	buffer_load_dwordx4 v[54:57], v46, s[60:63], s49 offen
	v_mad_u32_u16 v46, v48, s48, v90
	buffer_load_dwordx4 v[58:61], v46, s[60:63], s49 offen
	ds_read_b128 v[62:65], v45 offset:12224
	ds_read_b128 v[66:69], v44 offset:2608
	v_mad_u32_u16 v45, v49, s48, v90
	buffer_load_dwordx4 v[46:49], v45, s[60:63], s49 offen
	v_mov_b32_e32 v117, 0
	v_mov_b32_e32 v118, 0
	s_waitcnt vmcnt(8) lgkmcnt(1)
	v_dot4c_i32_i8_e32 v119, v0, v62
	s_waitcnt lgkmcnt(0)
	v_mad_u32_u16 v0, v66, s48, v90
	v_dot4c_i32_i8_e32 v116, v12, v62
	v_dot4c_i32_i8_e32 v117, v8, v62
	v_dot4c_i32_i8_e32 v118, v4, v62
	v_mad_u32_u16 v4, v67, s48, v90
	v_mad_u32_u16 v8, v68, s48, v90
	v_mad_u32_u16 v12, v69, s48, v90
	buffer_load_dwordx4 v[66:69], v0, s[60:63], s49 offen
	buffer_load_dwordx4 v[104:107], v4, s[60:63], s49 offen
	buffer_load_dwordx4 v[108:111], v8, s[60:63], s49 offen
	buffer_load_dwordx4 v[112:115], v12, s[60:63], s49 offen
	v_lshl_add_u64 v[40:41], v[78:79], 0, v[40:41]
	v_dot4c_i32_i8_e32 v117, v9, v63
	v_add_co_u32_e32 v70, vcc, s66, v40
	v_dot4c_i32_i8_e32 v117, v10, v64
	s_nop 0
	v_addc_co_u32_e32 v71, vcc, 0, v41, vcc
	v_dot4c_i32_i8_e32 v116, v13, v63
	v_dot4c_i32_i8_e32 v117, v11, v65
	global_load_dword v11, v[40:41], off
	global_load_dword v13, v[70:71], off
	v_dot4c_i32_i8_e32 v118, v5, v63
	v_dot4c_i32_i8_e32 v119, v1, v63
	v_dot4c_i32_i8_e32 v116, v14, v64
	v_dot4c_i32_i8_e32 v118, v6, v64
	v_dot4c_i32_i8_e32 v119, v2, v64
	v_mov_b32_e32 v120, 0
	v_mov_b32_e32 v121, 0
	v_mov_b32_e32 v122, 0
	v_mov_b32_e32 v123, 0
	v_dot4c_i32_i8_e32 v116, v15, v65
	v_dot4c_i32_i8_e32 v118, v7, v65
	v_dot4c_i32_i8_e32 v119, v3, v65
	v_mov_b32_e32 v124, 0
	v_mov_b32_e32 v8, 0
	v_cndmask_b32_e64 v0, v118, v116, s[2:3]
	v_cndmask_b32_e64 v1, v116, v118, s[2:3]
	v_cndmask_b32_e64 v2, v119, v117, s[2:3]
	v_cndmask_b32_e64 v3, v117, v119, s[2:3]
	v_add_u32_dpp v0, v1, v0 row_half_mirror row_mask:0xf bank_mask:0xf bound_ctrl:1
	v_mov_b32_e32 v9, 0
	v_add_u32_dpp v1, v3, v2 row_half_mirror row_mask:0xf bank_mask:0xf bound_ctrl:1
	v_cndmask_b32_e64 v2, v1, v0, s[4:5]
	v_cndmask_b32_e64 v0, v0, v1, s[4:5]
	v_mov_b32_e32 v12, 0
	v_mov_b32_e32 v14, 0
	v_add_u32_dpp v0, v0, v2 quad_perm:[2,3,0,1] row_mask:0xf bank_mask:0xf bound_ctrl:1
	ds_read2st64_b32 v[4:5], v96 offset0:12 offset1:13
	s_waitcnt vmcnt(13)
; __device__ __forceinline__ float row16_sum(float v) { v += dppf<0xB1>(v); v += dppf<0x4E>(v); v += dppf<0x141>(v); v += dppf<0x140>(v); return v; }
; __device__ __forceinline__ float row16_max(float v) { v = fmaxf(v, dppf<0xB1>(v)); v = fmaxf(v, dppf<0x4E>(v)); v = fmaxf(v, dppf<0x141>(v)); v = fmaxf(v, dppf<0x140>(v)); return v; }
; #define LAS __attribute__((address_space(3)))
; __device__ __forceinline__ void peer_block(int tok0, float* X1, const unsigned short* X1B, const int* TKI, const float* TKS, __amdgpu_buffer_rsrc_t U8r, __amdgpu_buffer_rsrc_t V6, const float* USC, const float* VSC,
;                                            const float* finw, pw_ptr L, int lane) {
;     ...
;     for (int t = 0; t < PT; ++t) {
;         const size_t tk = (size_t)(tok0 + t);
;         const float r = *(const LAS float*)(L + PW_R + t * 8), rx = *(const LAS float*)(L + PW_R + t * 8 + 4);
;         const int i0 = *(const LAS int*)(L + PW_REC + t * 512 + lane * 4), i1 = *(const LAS int*)(L + PW_REC + t * 512 + 256 + lane * 4);
;         const size_t rk0 = ((size_t)(lane >> 4) * M + tk) * 16 + (lane & 15), rk1 = rk0 + (size_t)4 * M * 16;
;         const float s0 = TKS[rk0] * r, s1 = TKS[rk1] * r;
;         const float e0 = __expf(s0 - row16_max(s0)), e1 = __expf(s1 - row16_max(s1));
;         const float g0 = e0 / row16_sum(e0), g1 = e1 / row16_sum(e1);
;         const f32x2c sc0 = *(const f32x2c*)(USC + 2 * i0), sc1 = *(const f32x2c*)(USC + 2 * i1);
;         const float a0 = (float)*(const LAS int*)(L + PW_ACT + t * 512 + lane * 4) * rx * sc0.x, a1 = (float)*(const LAS int*)(L + PW_ACT + t * 512 + 256 + lane * 4) * rx * sc1.x;
;         const float w0 = g0 * 0.5f * a0 * (1.0f + erff(a0 * 0.70710678118654752f)) * sc0.y, w1 = g1 * 0.5f * a1 * (1.0f + erff(a1 * 0.70710678118654752f)) * sc1.y;
	v_dot4c_i32_i8_e32 v120, v16, v62
	s_waitcnt vmcnt(12)
	v_dot4c_i32_i8_e32 v121, v20, v62
	s_waitcnt vmcnt(11)
	v_dot4c_i32_i8_e32 v122, v24, v62
	s_waitcnt vmcnt(10)
	v_dot4c_i32_i8_e32 v123, v28, v62
	v_dot4c_i32_i8_e32 v120, v17, v63
	v_dot4c_i32_i8_e32 v121, v21, v63
	v_dot4c_i32_i8_e32 v122, v25, v63
	v_dot4c_i32_i8_e32 v123, v29, v63
	v_dot4c_i32_i8_e32 v120, v18, v64
	v_dot4c_i32_i8_e32 v121, v22, v64
	v_dot4c_i32_i8_e32 v122, v26, v64
	v_dot4c_i32_i8_e32 v123, v30, v64
	v_dot4c_i32_i8_e32 v120, v19, v65
	v_dot4c_i32_i8_e32 v121, v23, v65
	v_dot4c_i32_i8_e32 v122, v27, v65
	v_dot4c_i32_i8_e32 v123, v31, v65
	v_add_u32_dpp v6, v0, v0 quad_perm:[1,0,3,2] row_mask:0xf bank_mask:0xf bound_ctrl:1
	s_waitcnt vmcnt(9)
	v_dot4c_i32_i8_e32 v124, v50, v62
	v_cndmask_b32_e64 v0, v122, v120, s[2:3]
	v_cndmask_b32_e64 v1, v120, v122, s[2:3]
	v_cndmask_b32_e64 v2, v123, v121, s[2:3]
	v_cndmask_b32_e64 v3, v121, v123, s[2:3]
	v_add_u32_dpp v0, v1, v0 row_half_mirror row_mask:0xf bank_mask:0xf bound_ctrl:1
	v_dot4c_i32_i8_e32 v124, v51, v63
	v_add_u32_dpp v1, v3, v2 row_half_mirror row_mask:0xf bank_mask:0xf bound_ctrl:1
	v_cndmask_b32_e64 v2, v1, v0, s[4:5]
	v_cndmask_b32_e64 v0, v0, v1, s[4:5]
	v_mov_b32_e32 v1, 0
	s_waitcnt vmcnt(7)
	v_dot4c_i32_i8_e32 v1, v58, v62
	v_add_u32_dpp v0, v0, v2 quad_perm:[2,3,0,1] row_mask:0xf bank_mask:0xf bound_ctrl:1
	v_mov_b32_e32 v2, 0
	v_dot4c_i32_i8_e32 v1, v59, v63
	v_add_u32_dpp v10, v0, v0 quad_perm:[1,0,3,2] row_mask:0xf bank_mask:0xf bound_ctrl:1
	v_mov_b32_e32 v0, 0
	v_dot4c_i32_i8_e32 v0, v54, v62
	s_waitcnt vmcnt(6)
	v_dot4c_i32_i8_e32 v2, v46, v62
	v_dot4c_i32_i8_e32 v124, v52, v64
	v_dot4c_i32_i8_e32 v0, v55, v63
	v_dot4c_i32_i8_e32 v1, v60, v64
	v_dot4c_i32_i8_e32 v2, v47, v63
	v_dot4c_i32_i8_e32 v124, v53, v65
	v_dot4c_i32_i8_e32 v0, v56, v64
	v_dot4c_i32_i8_e32 v1, v61, v65
	v_dot4c_i32_i8_e32 v2, v48, v64
	v_dot4c_i32_i8_e32 v0, v57, v65
	v_dot4c_i32_i8_e32 v2, v49, v65
	v_cndmask_b32_e64 v3, v1, v124, s[2:3]
	v_cndmask_b32_e64 v1, v124, v1, s[2:3]
	s_waitcnt vmcnt(5)
	v_dot4c_i32_i8_e32 v8, v66, v62
	s_waitcnt vmcnt(4)
	v_dot4c_i32_i8_e32 v9, v104, v62
	v_add_u32_dpp v1, v1, v3 row_half_mirror row_mask:0xf bank_mask:0xf bound_ctrl:1
	v_cndmask_b32_e64 v3, v2, v0, s[2:3]
	v_cndmask_b32_e64 v0, v0, v2, s[2:3]
	s_waitcnt vmcnt(3)
	v_dot4c_i32_i8_e32 v12, v108, v62
	s_waitcnt vmcnt(2)
	v_dot4c_i32_i8_e32 v14, v112, v62
	v_add_u32_dpp v0, v0, v3 row_half_mirror row_mask:0xf bank_mask:0xf bound_ctrl:1
	v_cndmask_b32_e64 v2, v0, v1, s[4:5]
	v_cndmask_b32_e64 v0, v1, v0, s[4:5]
	v_dot4c_i32_i8_e32 v8, v67, v63
	v_dot4c_i32_i8_e32 v9, v105, v63
	v_add_u32_dpp v0, v0, v2 quad_perm:[2,3,0,1] row_mask:0xf bank_mask:0xf bound_ctrl:1
	ds_read2st64_b32 v[2:3], v96 offset1:1
	v_dot4c_i32_i8_e32 v12, v109, v63
	v_add_u32_dpp v7, v0, v0 quad_perm:[1,0,3,2] row_mask:0xf bank_mask:0xf bound_ctrl:1
	v_dot4c_i32_i8_e32 v14, v113, v63
	v_dot4c_i32_i8_e32 v8, v68, v64
	s_waitcnt lgkmcnt(0)
	v_lshlrev_b32_e32 v0, 1, v2
	v_ashrrev_i32_e32 v1, 31, v0
	v_lshl_add_u64 v[0:1], v[0:1], 2, s[34:35]
	global_load_dwordx2 v[0:1], v[0:1], off
	v_lshlrev_b32_e32 v2, 1, v3
	v_ashrrev_i32_e32 v3, 31, v2
	v_lshl_add_u64 v[2:3], v[2:3], 2, s[34:35]
	global_load_dwordx2 v[2:3], v[2:3], off
	v_dot4c_i32_i8_e32 v9, v106, v64
	v_dot4c_i32_i8_e32 v12, v110, v64
	v_dot4c_i32_i8_e32 v14, v114, v64
	v_dot4c_i32_i8_e32 v8, v69, v65
	v_dot4c_i32_i8_e32 v9, v107, v65
	v_dot4c_i32_i8_e32 v12, v111, v65
	v_dot4c_i32_i8_e32 v14, v115, v65
	s_nop 1
	v_cndmask_b32_e64 v15, v12, v8, s[2:3]
	v_cndmask_b32_e64 v8, v8, v12, s[2:3]
	v_cndmask_b32_e64 v12, v14, v9, s[2:3]
	v_cndmask_b32_e64 v9, v9, v14, s[2:3]
	v_add_u32_dpp v8, v8, v15 row_half_mirror row_mask:0xf bank_mask:0xf bound_ctrl:1
	v_add_u32_e32 v14, 0x1400, v100
	v_add_u32_dpp v9, v9, v12 row_half_mirror row_mask:0xf bank_mask:0xf bound_ctrl:1
	v_cndmask_b32_e64 v12, v9, v8, s[4:5]
	v_cndmask_b32_e64 v8, v8, v9, s[4:5]
	v_cndmask_b32_e64 v15, v7, v6, s[6:7]
	v_mov_b32_e32 v6, s33
	v_add_u32_dpp v12, v8, v12 quad_perm:[2,3,0,1] row_mask:0xf bank_mask:0xf bound_ctrl:1
	ds_read2_b32 v[8:9], v14 offset0:128 offset1:132
	ds_read_b64 v[6:7], v6 offset:6144
	v_add_u32_dpp v12, v12, v12 quad_perm:[1,0,3,2] row_mask:0xf bank_mask:0xf bound_ctrl:1
	v_cndmask_b32_e64 v10, v12, v10, s[6:7]
	s_waitcnt lgkmcnt(1)
	v_add_u32_e32 v8, v8, v15
	v_add_u32_e32 v9, v9, v10
	ds_write2_b32 v14, v8, v9 offset0:128 offset1:132
	s_waitcnt vmcnt(3) lgkmcnt(1)
	v_mul_f32_e32 v8, v6, v11
	s_waitcnt vmcnt(2)
	v_mul_f32_e32 v9, v6, v13
	v_mov_b32_dpp v10, v8 quad_perm:[1,0,3,2] row_mask:0xf bank_mask:0xf bound_ctrl:1
	v_max_f32_e32 v10, v10, v10
	v_max_f32_e32 v8, v8, v10
	s_nop 1
	v_mov_b32_dpp v10, v8 quad_perm:[2,3,0,1] row_mask:0xf bank_mask:0xf bound_ctrl:1
	v_max_f32_e32 v10, v10, v10
	v_max_f32_e32 v8, v8, v10
	s_nop 1
	v_mov_b32_dpp v10, v8 row_half_mirror row_mask:0xf bank_mask:0xf bound_ctrl:1
	v_max_f32_e32 v10, v10, v10
	v_max_f32_e32 v8, v8, v10
	s_nop 1
	v_mov_b32_dpp v10, v8 row_mirror row_mask:0xf bank_mask:0xf bound_ctrl:1
	v_max_f32_e32 v10, v10, v10
	v_max_f32_e32 v8, v8, v10
	v_fma_f32 v8, v6, v11, -v8
	v_mul_f32_e32 v8, 0x3fb8aa3b, v8
	v_exp_f32_e32 v12, v8
	v_cvt_f32_i32_e32 v10, v4
	v_mov_b32_dpp v8, v9 quad_perm:[1,0,3,2] row_mask:0xf bank_mask:0xf bound_ctrl:1
	v_max_f32_e32 v8, v8, v8
	v_max_f32_e32 v8, v9, v8
	v_mul_f32_e32 v10, v7, v10
	s_waitcnt vmcnt(1)
	v_mul_f32_e32 v0, v0, v10
	v_mov_b32_dpp v9, v8 quad_perm:[2,3,0,1] row_mask:0xf bank_mask:0xf bound_ctrl:1
	v_max_f32_e32 v9, v9, v9
	v_max_f32_e32 v8, v8, v9
	v_mul_f32_e32 v10, 0x3f3504f3, v0
	v_cmp_nlt_f32_e64 s[10:11], |v10|, 1.0
	v_mov_b32_dpp v9, v8 row_half_mirror row_mask:0xf bank_mask:0xf bound_ctrl:1
	v_max_f32_e32 v9, v9, v9
	v_max_f32_e32 v8, v8, v9
	s_nop 1
	v_mov_b32_dpp v9, v8 row_mirror row_mask:0xf bank_mask:0xf bound_ctrl:1
	v_max_f32_e32 v9, v9, v9
	v_max_f32_e32 v8, v8, v9
	v_fma_f32 v6, v6, v13, -v8
	v_mul_f32_e32 v6, 0x3fb8aa3b, v6
	v_exp_f32_e32 v13, v6
	s_nop 0
	v_add_f32_dpp v6, v12, v12 quad_perm:[1,0,3,2] row_mask:0xf bank_mask:0xf bound_ctrl:1
	v_add_f32_dpp v9, v13, v13 quad_perm:[1,0,3,2] row_mask:0xf bank_mask:0xf bound_ctrl:1
	s_nop 0
	v_add_f32_dpp v6, v6, v6 quad_perm:[2,3,0,1] row_mask:0xf bank_mask:0xf bound_ctrl:1
	v_add_f32_dpp v4, v9, v9 quad_perm:[2,3,0,1] row_mask:0xf bank_mask:0xf bound_ctrl:1
	s_nop 0
	v_add_f32_dpp v6, v6, v6 row_half_mirror row_mask:0xf bank_mask:0xf bound_ctrl:1
	v_add_f32_dpp v4, v4, v4 row_half_mirror row_mask:0xf bank_mask:0xf bound_ctrl:1
	s_nop 0
	v_mov_b32_dpp v8, v6 row_mirror row_mask:0xf bank_mask:0xf bound_ctrl:1
	v_mov_b32_dpp v9, v4 row_mirror row_mask:0xf bank_mask:0xf bound_ctrl:1
	s_and_saveexec_b64 s[40:41], s[10:11]
	s_xor_b64 s[10:11], exec, s[40:41]
	s_cbranch_execz .LBB0_695
; __device__ __forceinline__ void peer_block(int tok0, float* X1, const unsigned short* X1B, const int* TKI, const float* TKS, __amdgpu_buffer_rsrc_t U8r, __amdgpu_buffer_rsrc_t V6, const float* USC, const float* VSC,
;                                            const float* finw, pw_ptr L, int lane) {
;     ...
;         const float w0 = g0 * 0.5f * a0 * (1.0f + erff(a0 * 0.70710678118654752f)) * sc0.y, w1 = g1 * 0.5f * a1 * (1.0f + erff(a1 * 0.70710678118654752f)) * sc1.y;
	v_fma_f32 v11, |v10|, s50, v102
	v_fma_f32 v11, |v10|, v11, s51
	v_fma_f32 v11, |v10|, v11, s52
	v_fma_f32 v11, |v10|, v11, s53
	v_fma_f32 v11, |v10|, v11, s54
	v_fma_f32 v11, |v10|, v11, s55
	v_fma_f32 v11, |v10|, v11, |v10|
	v_mul_f32_e32 v14, 0xbfb8aa3b, v11
	v_fma_f32 v15, v11, s56, -v14
	v_rndne_f32_e32 v16, v14
	v_fmac_f32_e32 v15, 0xb2a5705f, v11
	v_sub_f32_e32 v14, v14, v16
	v_add_f32_e32 v14, v14, v15
	v_cvt_i32_f32_e32 v15, v16
	v_exp_f32_e32 v14, v14
	v_cmp_nlt_f32_e32 vcc, s57, v11
	v_ldexp_f32 v14, v14, v15
	s_nop 0
	v_cndmask_b32_e32 v14, 0, v14, vcc
	v_cmp_ngt_f32_e32 vcc, s58, v11
	s_nop 1
	v_cndmask_b32_e32 v11, v103, v14, vcc
	v_sub_f32_e32 v11, 1.0, v11

; #define LAS __attribute__((address_space(3)))
; __device__ __forceinline__ H16x2 peer_cvt6h(const Row6& r) { return __builtin_bit_cast(H16x2, __builtin_amdgcn_cvt_scalef32_pk32_f16_fp6(r.d, 1.0f)); }
; #define PB_RECS(rv, t, q) do { rv = *(const LAS recv_t*)(L + PW_REC + (t) * 512 + (g16 + NPB * (q)) * 4); } while (0)
; template <bool FIRST>
; __device__ __forceinline__ void pb_v_part(const Row6 (&buf)[NPB], const wv_t& rv, h2g (&acc)[16]) {
; #pragma unroll
;     for (int i = 0; i < NPB; ++i) { Row6 rr = buf[i]; const unsigned wu = rv[i]; const h2g w2 = __builtin_bit_cast(h2g, wu);
;         if (FIRST && i == 0) {
;             const H16x2 v = peer_cvt6h(rr);
; #pragma unroll
;             for (int k = 0; k < 16; ++k) acc[k] = w2 * v.p[k];
;         } else {
;             asm volatile("" : "+v"(rr.d) : "v"(acc[0]), "v"(acc[1]), "v"(acc[2]), "v"(acc[3]), "v"(acc[4]), "v"(acc[5]), "v"(acc[6]), "v"(acc[7]), "v"(acc[8]), "v"(acc[9]), "v"(acc[10]), "v"(acc[11]), "v"(acc[12]), "v"(acc[13]), "v"(acc[14]), "v"(acc[15]));
;             peer_axpy(rr, w2, acc); }
;         __builtin_amdgcn_sched_barrier(0); }
; __device__ __forceinline__ void peer_block(int tok0, float* X1, const unsigned short* X1B, const int* TKI, const float* TKS, __amdgpu_buffer_rsrc_t U8r, __amdgpu_buffer_rsrc_t V6, const float* USC, const float* VSC,
;                                            const float* finw, pw_ptr L, int lane) {
;     ...
;         for (int it = 0; it < 4 * PT; ++it) {
;             const int c = it / PT, t = it - c * PT; const int soff = c * SLB;
;             const int itn = it + 1, cn = itn / PT, tn = itn - cn * PT;
;             h2g acc[16];
; #pragma unroll
;             for (int q = 0; q < NQ; ++q) {
;                 const int qa = q + NB - 1;
;                 if (qa < NQ) { PB_RECS(rv, t, qa); PB_LOAD(bb[qa % NB], V6, rv, soff); }
;                 else if (itn < 4 * PT) { PB_RECS(rv, tn, qa - NQ); PB_LOAD(bb[qa % NB], V6, rv, cn * SLB); }
;                 wv_t rw = *(const LAS wv_t*)(L + PW_ACT + t * 512 + (g16 + NPB * q) * 4); if (q == 0) pb_v_part<true>(bb[q % NB], rw, acc); else pb_v_part<false>(bb[q % NB], rw, acc);
;             }
.LBB0_743:
	s_mul_hi_u32 s68, s41, 0xaaaaaaab
	s_lshr_b32 s68, s68, 2
	s_mul_i32 s69, s68, 6
	s_cmp_eq_u32 s69, s41
	s_cbranch_scc0 .Lpv_nosync
	s_barrier
.Lpv_nosync:
	s_mul_i32 s69, s68, 0xc00
	v_subrev_u32_e32 v0, s69, v91
	s_mul_i32 s69, s11, 0xab
	s_add_i32 s70, s33, s40
	v_add_u32_e32 v104, s70, v0
	s_add_i32 s71, s69, 0xff55
	ds_read_b128 v[0:3], v104 offset:16
	ds_read_b128 v[64:67], v104 offset:3072
	s_bfe_u32 s71, s71, 0x6000a
	s_mul_i32 s71, s71, 0x300000
	s_waitcnt lgkmcnt(1)
	v_mad_u32_u16 v4, v0, s48, v90
	v_mad_u32_u16 v0, v0, s42, v92
	buffer_load_dwordx4 v[40:43], v4, s[64:67], s71 offen
	buffer_load_dwordx2 v[44:45], v0, s[64:67], s71 offen
	v_mad_u32_u16 v0, v1, s48, v90
	v_mad_u32_u16 v1, v1, s42, v92
	buffer_load_dwordx4 v[46:49], v0, s[64:67], s71 offen
	buffer_load_dwordx2 v[50:51], v1, s[64:67], s71 offen
	v_mad_u32_u16 v0, v2, s48, v90
	v_mad_u32_u16 v1, v2, s42, v92
	buffer_load_dwordx4 v[52:55], v0, s[64:67], s71 offen
	buffer_load_dwordx2 v[56:57], v1, s[64:67], s71 offen
	v_mad_u32_u16 v0, v3, s48, v90
	v_mad_u32_u16 v1, v3, s42, v92
	buffer_load_dwordx4 v[58:61], v0, s[64:67], s71 offen
	buffer_load_dwordx2 v[62:63], v1, s[64:67], s71 offen
	s_waitcnt vmcnt(14)
	v_cvt_scalef32_pk32_f16_fp6 v[0:15], v[28:33], 1.0
	s_waitcnt lgkmcnt(0)
	v_pk_mul_f16 v28, v0, v64
	v_pk_mul_f16 v29, v1, v64
	v_pk_mul_f16 v30, v2, v64
	v_pk_mul_f16 v31, v3, v64
	v_pk_mul_f16 v32, v4, v64
	v_pk_mul_f16 v33, v5, v64
	v_pk_mul_f16 v68, v6, v64
	v_pk_mul_f16 v69, v7, v64
	v_pk_mul_f16 v70, v8, v64
	v_pk_mul_f16 v71, v9, v64
	v_pk_mul_f16 v105, v10, v64
	v_pk_mul_f16 v106, v11, v64
	v_pk_mul_f16 v107, v12, v64
	v_pk_mul_f16 v108, v13, v64
	v_pk_mul_f16 v109, v14, v64
	v_pk_mul_f16 v64, v15, v64
	s_cmpk_eq_i32 s40, 0x2e00
	s_waitcnt vmcnt(12)
	s_nop 0
	v_cvt_scalef32_pk32_f16_fp6 v[0:15], v[16:21], 1.0
	v_pk_fma_f16 v16, v65, v0, v28
	v_pk_fma_f16 v17, v65, v1, v29
	v_pk_fma_f16 v18, v65, v2, v30
	v_pk_fma_f16 v19, v65, v3, v31
	v_pk_fma_f16 v20, v65, v4, v32
	v_pk_fma_f16 v21, v65, v5, v33
	v_pk_fma_f16 v28, v65, v6, v68
	v_pk_fma_f16 v29, v65, v7, v69
	v_pk_fma_f16 v30, v65, v8, v70
	v_pk_fma_f16 v31, v65, v9, v71
	v_pk_fma_f16 v32, v65, v10, v105
	v_pk_fma_f16 v33, v65, v11, v106
	v_pk_fma_f16 v68, v65, v12, v107
	v_pk_fma_f16 v69, v65, v13, v108
	v_pk_fma_f16 v70, v65, v14, v109
	v_pk_fma_f16 v64, v65, v15, v64
	s_waitcnt vmcnt(10)
	s_nop 0
	v_cvt_scalef32_pk32_f16_fp6 v[0:15], v[22:27], 1.0
	v_pk_fma_f16 v16, v66, v0, v16
	v_pk_fma_f16 v17, v66, v1, v17
	v_pk_fma_f16 v18, v66, v2, v18
	v_pk_fma_f16 v19, v66, v3, v19
	v_pk_fma_f16 v20, v66, v4, v20
	v_pk_fma_f16 v21, v66, v5, v21
	v_pk_fma_f16 v22, v66, v6, v28
	v_pk_fma_f16 v23, v66, v7, v29
	v_pk_fma_f16 v24, v66, v8, v30
	v_pk_fma_f16 v25, v66, v9, v31
	v_pk_fma_f16 v26, v66, v10, v32
	v_pk_fma_f16 v27, v66, v11, v33
	v_pk_fma_f16 v28, v66, v12, v68
	v_pk_fma_f16 v29, v66, v13, v69
	v_pk_fma_f16 v30, v66, v14, v70
	v_pk_fma_f16 v31, v66, v15, v64
	s_waitcnt vmcnt(8)
	s_nop 0
	v_cvt_scalef32_pk32_f16_fp6 v[0:15], v[34:39], 1.0
	v_pk_fma_f16 v68, v67, v0, v16
	v_pk_fma_f16 v69, v67, v1, v17
	v_pk_fma_f16 v70, v67, v2, v18
	v_pk_fma_f16 v71, v67, v3, v19
	v_pk_fma_f16 v105, v67, v4, v20
	v_pk_fma_f16 v106, v67, v5, v21
	v_pk_fma_f16 v107, v67, v6, v22
	v_pk_fma_f16 v108, v67, v7, v23
	v_pk_fma_f16 v109, v67, v8, v24
	v_pk_fma_f16 v110, v67, v9, v25
	v_pk_fma_f16 v111, v67, v10, v26
	v_pk_fma_f16 v112, v67, v11, v27
	v_pk_fma_f16 v113, v67, v12, v28
	v_pk_fma_f16 v114, v67, v13, v29
	v_pk_fma_f16 v115, v67, v14, v30
	v_pk_fma_f16 v116, v67, v15, v31
	ds_read_b128 v[0:3], v104 offset:32
	ds_read_b128 v[64:67], v104 offset:3088
	s_waitcnt lgkmcnt(1)
	v_mad_u32_u16 v4, v0, s48, v90
	v_mad_u32_u16 v0, v0, s42, v92
	v_mad_u32_u16 v5, v1, s48, v90
	buffer_load_dwordx4 v[28:31], v4, s[64:67], s71 offen
	buffer_load_dwordx2 v[32:33], v0, s[64:67], s71 offen
	v_mad_u32_u16 v0, v1, s42, v92
	buffer_load_dwordx4 v[16:19], v5, s[64:67], s71 offen
	buffer_load_dwordx2 v[20:21], v0, s[64:67], s71 offen
	v_mad_u32_u16 v0, v2, s48, v90
	v_mad_u32_u16 v1, v2, s42, v92
	buffer_load_dwordx4 v[22:25], v0, s[64:67], s71 offen
	buffer_load_dwordx2 v[26:27], v1, s[64:67], s71 offen
	v_mad_u32_u16 v0, v3, s48, v90
	v_mad_u32_u16 v1, v3, s42, v92
	buffer_load_dwordx4 v[34:37], v0, s[64:67], s71 offen
	buffer_load_dwordx2 v[38:39], v1, s[64:67], s71 offen
	s_waitcnt vmcnt(14)
	s_nop 0
	v_cvt_scalef32_pk32_f16_fp6 v[0:15], v[40:45], 1.0
	s_waitcnt lgkmcnt(0)
	v_pk_fma_f16 v40, v64, v0, v68
	v_pk_fma_f16 v41, v64, v1, v69
	v_pk_fma_f16 v42, v64, v2, v70
	v_pk_fma_f16 v43, v64, v3, v71
	v_pk_fma_f16 v44, v64, v4, v105
	v_pk_fma_f16 v45, v64, v5, v106
	v_pk_fma_f16 v68, v64, v6, v107
	v_pk_fma_f16 v69, v64, v7, v108
	v_pk_fma_f16 v70, v64, v8, v109
	v_pk_fma_f16 v71, v64, v9, v110
	v_pk_fma_f16 v105, v64, v10, v111
	v_pk_fma_f16 v106, v64, v11, v112
	v_pk_fma_f16 v107, v64, v12, v113
	v_pk_fma_f16 v108, v64, v13, v114
	v_pk_fma_f16 v109, v64, v14, v115
	v_pk_fma_f16 v64, v64, v15, v116
	s_waitcnt vmcnt(12)
	s_nop 0
	v_cvt_scalef32_pk32_f16_fp6 v[0:15], v[46:51], 1.0
	v_pk_fma_f16 v40, v65, v0, v40
	v_pk_fma_f16 v41, v65, v1, v41
	v_pk_fma_f16 v42, v65, v2, v42
	v_pk_fma_f16 v43, v65, v3, v43
	v_pk_fma_f16 v44, v65, v4, v44
	v_pk_fma_f16 v45, v65, v5, v45
	v_pk_fma_f16 v46, v65, v6, v68
	v_pk_fma_f16 v47, v65, v7, v69
	v_pk_fma_f16 v48, v65, v8, v70
	v_pk_fma_f16 v49, v65, v9, v71
	v_pk_fma_f16 v50, v65, v10, v105
	v_pk_fma_f16 v51, v65, v11, v106
	v_pk_fma_f16 v68, v65, v12, v107
	v_pk_fma_f16 v69, v65, v13, v108
	v_pk_fma_f16 v70, v65, v14, v109
	v_pk_fma_f16 v64, v65, v15, v64
	s_waitcnt vmcnt(10)
; #define LAS __attribute__((address_space(3)))
; __device__ __forceinline__ H16x2 peer_cvt6h(const Row6& r) { return __builtin_bit_cast(H16x2, __builtin_amdgcn_cvt_scalef32_pk32_f16_fp6(r.d, 1.0f)); }
; #define PB_RECS(rv, t, q) do { rv = *(const LAS recv_t*)(L + PW_REC + (t) * 512 + (g16 + NPB * (q)) * 4); } while (0)
; __device__ __forceinline__ void peer_axpy(const Row6& r, h2g w2, h2g (&acc)[16]) {
;     const H16x2 v = peer_cvt6h(r);
; #pragma unroll
;     for (int k = 0; k < 16; ++k) acc[k] = __builtin_elementwise_fma(w2, v.p[k], acc[k]);
; }
; __device__ __forceinline__ void peer_block(int tok0, float* X1, const unsigned short* X1B, const int* TKI, const float* TKS, __amdgpu_buffer_rsrc_t U8r, __amdgpu_buffer_rsrc_t V6, const float* USC, const float* VSC,
;                                            const float* finw, pw_ptr L, int lane) {
;     ...
;         for (int it = 0; it < 4 * PT; ++it) {
;             const int c = it / PT, t = it - c * PT; const int soff = c * SLB;
;             const int itn = it + 1, cn = itn / PT, tn = itn - cn * PT;
;             h2g acc[16];
; #pragma unroll
;             for (int q = 0; q < NQ; ++q) {
;                 const int qa = q + NB - 1;
;                 if (qa < NQ) { PB_RECS(rv, t, qa); PB_LOAD(bb[qa % NB], V6, rv, soff); }
;                 else if (itn < 4 * PT) { PB_RECS(rv, tn, qa - NQ); PB_LOAD(bb[qa % NB], V6, rv, cn * SLB); }
;                 wv_t rw = *(const LAS wv_t*)(L + PW_ACT + t * 512 + (g16 + NPB * q) * 4); if (q == 0) pb_v_part<true>(bb[q % NB], rw, acc); else pb_v_part<false>(bb[q % NB], rw, acc);
;             }
	s_nop 0
	v_cvt_scalef32_pk32_f16_fp6 v[0:15], v[52:57], 1.0
	v_pk_fma_f16 v40, v66, v0, v40
	v_pk_fma_f16 v41, v66, v1, v41
	v_pk_fma_f16 v42, v66, v2, v42
	v_pk_fma_f16 v43, v66, v3, v43
	v_pk_fma_f16 v44, v66, v4, v44
	v_pk_fma_f16 v45, v66, v5, v45
	v_pk_fma_f16 v46, v66, v6, v46
	v_pk_fma_f16 v47, v66, v7, v47
	v_pk_fma_f16 v48, v66, v8, v48
	v_pk_fma_f16 v49, v66, v9, v49
	v_pk_fma_f16 v50, v66, v10, v50
	v_pk_fma_f16 v51, v66, v11, v51
	v_pk_fma_f16 v52, v66, v12, v68
	v_pk_fma_f16 v53, v66, v13, v69
	v_pk_fma_f16 v54, v66, v14, v70
	v_pk_fma_f16 v55, v66, v15, v64
	s_waitcnt vmcnt(8)
	s_nop 0
	v_cvt_scalef32_pk32_f16_fp6 v[0:15], v[58:63], 1.0
	v_pk_fma_f16 v64, v67, v0, v40
	v_pk_fma_f16 v65, v67, v1, v41
	v_pk_fma_f16 v66, v67, v2, v42
	v_pk_fma_f16 v105, v67, v3, v43
	v_pk_fma_f16 v112, v67, v4, v44
	v_pk_fma_f16 v113, v67, v5, v45
	v_pk_fma_f16 v114, v67, v6, v46
	v_pk_fma_f16 v115, v67, v7, v47
	v_pk_fma_f16 v116, v67, v8, v48
	v_pk_fma_f16 v117, v67, v9, v49
	v_pk_fma_f16 v118, v67, v10, v50
	v_pk_fma_f16 v119, v67, v11, v51
	v_pk_fma_f16 v120, v67, v12, v52
	v_pk_fma_f16 v121, v67, v13, v53
	v_pk_fma_f16 v122, v67, v14, v54
	v_pk_fma_f16 v67, v67, v15, v55
	ds_read_b128 v[0:3], v104 offset:48
	ds_read_b128 v[68:71], v104 offset:3104
	s_waitcnt vmcnt(6)
	v_mov_b64_e32 v[110:111], v[32:33]
	v_mov_b64_e32 v[108:109], v[30:31]
	v_mov_b64_e32 v[106:107], v[28:29]
	s_waitcnt lgkmcnt(1)
	v_mad_u32_u16 v4, v0, s48, v90
	v_mad_u32_u16 v0, v0, s42, v92
	v_mad_u32_u16 v5, v1, s48, v90
	buffer_load_dwordx4 v[58:61], v4, s[64:67], s71 offen
	buffer_load_dwordx2 v[62:63], v0, s[64:67], s71 offen
	v_mad_u32_u16 v0, v1, s42, v92
	buffer_load_dwordx4 v[52:55], v5, s[64:67], s71 offen
	buffer_load_dwordx2 v[56:57], v0, s[64:67], s71 offen
	v_mad_u32_u16 v0, v2, s48, v90
	v_mad_u32_u16 v1, v2, s42, v92
	buffer_load_dwordx4 v[46:49], v0, s[64:67], s71 offen
	buffer_load_dwordx2 v[50:51], v1, s[64:67], s71 offen
	v_mad_u32_u16 v0, v3, s48, v90
	v_mad_u32_u16 v1, v3, s42, v92
	buffer_load_dwordx4 v[40:43], v0, s[64:67], s71 offen
	buffer_load_dwordx2 v[44:45], v1, s[64:67], s71 offen
	s_nop 0
	v_cvt_scalef32_pk32_f16_fp6 v[0:15], v[106:111], 1.0
	s_waitcnt lgkmcnt(0)
	v_pk_fma_f16 v64, v68, v0, v64
	v_pk_fma_f16 v65, v68, v1, v65
	v_pk_fma_f16 v66, v68, v2, v66
	v_pk_fma_f16 v105, v68, v3, v105
	v_pk_fma_f16 v112, v68, v4, v112
	v_pk_fma_f16 v113, v68, v5, v113
	v_pk_fma_f16 v114, v68, v6, v114
	v_pk_fma_f16 v115, v68, v7, v115
	v_pk_fma_f16 v116, v68, v8, v116
	v_pk_fma_f16 v117, v68, v9, v117
	v_pk_fma_f16 v118, v68, v10, v118
	v_pk_fma_f16 v119, v68, v11, v119
	v_pk_fma_f16 v67, v68, v15, v67
	v_pk_fma_f16 v120, v68, v12, v120
	v_pk_fma_f16 v121, v68, v13, v121
	v_pk_fma_f16 v122, v68, v14, v122
	s_waitcnt vmcnt(12)
	v_mov_b64_e32 v[110:111], v[20:21]
	v_mov_b64_e32 v[108:109], v[18:19]
	v_mov_b64_e32 v[106:107], v[16:17]
	s_nop 0
	v_cvt_scalef32_pk32_f16_fp6 v[0:15], v[106:111], 1.0
	v_pk_fma_f16 v106, v69, v0, v64
	v_pk_fma_f16 v107, v69, v1, v65
	v_pk_fma_f16 v108, v69, v2, v66
	v_pk_fma_f16 v105, v69, v3, v105
	v_pk_fma_f16 v110, v69, v4, v112
	v_pk_fma_f16 v111, v69, v5, v113
	v_pk_fma_f16 v112, v69, v6, v114
	v_pk_fma_f16 v113, v69, v7, v115
	v_pk_fma_f16 v114, v69, v8, v116
	v_pk_fma_f16 v115, v69, v9, v117
	v_pk_fma_f16 v116, v69, v10, v118
	v_pk_fma_f16 v117, v69, v11, v119
	v_pk_fma_f16 v118, v69, v12, v120
	v_pk_fma_f16 v119, v69, v13, v121
	v_pk_fma_f16 v120, v69, v14, v122
	v_pk_fma_f16 v121, v69, v15, v67
	s_waitcnt vmcnt(10)
	v_mov_b64_e32 v[68:69], v[26:27]
	v_mov_b64_e32 v[66:67], v[24:25]
	v_mov_b64_e32 v[64:65], v[22:23]
	s_nop 0
	v_cvt_scalef32_pk32_f16_fp6 v[0:15], v[64:69], 1.0
	v_pk_fma_f16 v106, v70, v0, v106
	v_pk_fma_f16 v107, v70, v1, v107
	v_pk_fma_f16 v108, v70, v2, v108
	v_pk_fma_f16 v109, v70, v3, v105
	v_pk_fma_f16 v110, v70, v4, v110
	v_pk_fma_f16 v111, v70, v5, v111
	v_pk_fma_f16 v112, v70, v6, v112
	v_pk_fma_f16 v113, v70, v7, v113
	v_pk_fma_f16 v114, v70, v8, v114
	v_pk_fma_f16 v115, v70, v9, v115
	v_pk_fma_f16 v116, v70, v10, v116
	v_pk_fma_f16 v117, v70, v11, v117
	v_pk_fma_f16 v118, v70, v12, v118
	v_pk_fma_f16 v119, v70, v13, v119
	v_pk_fma_f16 v105, v70, v14, v120
	v_pk_fma_f16 v70, v70, v15, v121
	s_waitcnt vmcnt(8)
	v_mov_b64_e32 v[68:69], v[38:39]
	v_mov_b64_e32 v[66:67], v[36:37]
	v_mov_b64_e32 v[64:65], v[34:35]
	s_cbranch_scc1 .LBB0_742
	s_mul_hi_u32 s71, s11, 0xaaaaaaab
	s_lshr_b32 s71, s71, 2
	s_mulk_i32 s71, 0xc00
	v_subrev_u32_e32 v0, s71, v83
	v_add_u32_e32 v0, s70, v0
	ds_read_b128 v[0:3], v0
	s_bfe_u32 s69, s69, 0x6000a
	s_mul_i32 s69, s69, 0x300000
	s_waitcnt lgkmcnt(0)
	v_mad_u32_u16 v4, v0, s48, v90
	v_mad_u32_u16 v0, v0, s42, v92
	buffer_load_dwordx4 v[28:31], v4, s[64:67], s69 offen
	buffer_load_dwordx2 v[32:33], v0, s[64:67], s69 offen
	v_mad_u32_u16 v0, v1, s48, v90
	v_mad_u32_u16 v1, v1, s42, v92
	buffer_load_dwordx4 v[16:19], v0, s[64:67], s69 offen
	buffer_load_dwordx2 v[20:21], v1, s[64:67], s69 offen
	v_mad_u32_u16 v0, v2, s48, v90
	v_mad_u32_u16 v1, v2, s42, v92
	buffer_load_dwordx4 v[22:25], v0, s[64:67], s69 offen
	buffer_load_dwordx2 v[26:27], v1, s[64:67], s69 offen
	v_mad_u32_u16 v0, v3, s48, v90
	v_mad_u32_u16 v1, v3, s42, v92
	buffer_load_dwordx4 v[34:37], v0, s[64:67], s69 offen
	buffer_load_dwordx2 v[38:39], v1, s[64:67], s69 offen
	s_branch .LBB0_742

; __global__ void __launch_bounds__(NWAVES * 64, 2) mk_fwd(Params P) {
	.amdhsa_kernel _Z6mk_fwd6Params
		.amdhsa_group_segment_fixed_size 0
		.amdhsa_private_segment_fixed_size 0
		.amdhsa_kernarg_size 424
		.amdhsa_user_sgpr_count 2
		.amdhsa_user_sgpr_dispatch_ptr 0
		.amdhsa_user_sgpr_queue_ptr 0
		.amdhsa_user_sgpr_kernarg_segment_ptr 1
		.amdhsa_user_sgpr_dispatch_id 0
		.amdhsa_user_sgpr_kernarg_preload_length 0
		.amdhsa_user_sgpr_kernarg_preload_offset 0
		.amdhsa_user_sgpr_private_segment_size 0
		.amdhsa_uses_dynamic_stack 0
		.amdhsa_enable_private_segment 0
		.amdhsa_system_sgpr_workgroup_id_x 1
		.amdhsa_system_sgpr_workgroup_id_y 0
		.amdhsa_system_sgpr_workgroup_id_z 0
		.amdhsa_system_sgpr_workgroup_info 0
		.amdhsa_system_vgpr_workitem_id 2
		.amdhsa_next_free_vgpr 256
		.amdhsa_next_free_sgpr 102
		.amdhsa_accum_offset 256
		.amdhsa_reserve_vcc 1
		.amdhsa_float_round_mode_32 0
		.amdhsa_float_round_mode_16_64 0
		.amdhsa_float_denorm_mode_32 3
		.amdhsa_float_denorm_mode_16_64 3
		.amdhsa_dx10_clamp 1
		.amdhsa_ieee_mode 1
		.amdhsa_fp16_overflow 0
		.amdhsa_tg_split 0
		.amdhsa_exception_fp_ieee_invalid_op 0
		.amdhsa_exception_fp_denorm_src 0
		.amdhsa_exception_fp_ieee_div_zero 0
		.amdhsa_exception_fp_ieee_overflow 0
		.amdhsa_exception_fp_ieee_underflow 0
		.amdhsa_exception_fp_ieee_inexact 0
		.amdhsa_exception_int_div_zero 0
	.end_amdhsa_kernel

; __global__ void __launch_bounds__(NWAVES * 64, 2) mk_fwd(Params P) {
amdhsa.kernels:
  - .agpr_count:     0
    .args:
      - .offset:         0
        .size:           168
        .value_kind:     by_value
      - .offset:         168
        .size:           4
        .value_kind:     hidden_block_count_x
      - .offset:         172
        .size:           4
        .value_kind:     hidden_block_count_y
      - .offset:         176
        .size:           4
        .value_kind:     hidden_block_count_z
      - .offset:         180
        .size:           2
        .value_kind:     hidden_group_size_x
      - .offset:         182
        .size:           2
        .value_kind:     hidden_group_size_y
      - .offset:         184
        .size:           2
        .value_kind:     hidden_group_size_z
      - .offset:         186
        .size:           2
        .value_kind:     hidden_remainder_x
      - .offset:         188
        .size:           2
        .value_kind:     hidden_remainder_y
      - .offset:         190
        .size:           2
        .value_kind:     hidden_remainder_z
      - .offset:         208
        .size:           8
        .value_kind:     hidden_global_offset_x
      - .offset:         216
        .size:           8
        .value_kind:     hidden_global_offset_y
      - .offset:         224
        .size:           8
        .value_kind:     hidden_global_offset_z
      - .offset:         232
        .size:           2
        .value_kind:     hidden_grid_dims
      - .offset:         256
        .size:           8
        .value_kind:     hidden_multigrid_sync_arg
      - .offset:         288
        .size:           4
        .value_kind:     hidden_dynamic_lds_size
    .group_segment_fixed_size: 0
    .kernarg_segment_align: 8
    .kernarg_segment_size: 424
    .language:       OpenCL C
    .language_version:
      - 2
      - 0
    .max_flat_workgroup_size: 512
    .name:           _Z6mk_fwd6Params
    .private_segment_fixed_size: 0
    .sgpr_count:     108
    .sgpr_spill_count: 22
    .symbol:         _Z6mk_fwd6Params.kd
    .uniform_work_group_size: 1
    .uses_dynamic_stack: false
    .vgpr_count:     256
    .vgpr_spill_count: 0
    .wavefront_size: 64
